# GEMM K-loops: LDS-DMA loads in saddr form (SGPR base plus 32-bit lane offset), 6 to 8 fewer 64-bit VALU adds per iteration (measurement 1)
# speedup vs baseline: 1.0040x; 1.0040x over previous
.LBB0_294:
	ds_read_b128 v[154:157], v151
	ds_read_b128 v[158:161], v151 offset:1024
	ds_read_b128 v[162:165], v151 offset:2048
	ds_read_b128 v[166:169], v151 offset:3072
	ds_read_b128 v[170:173], v152
	ds_read_b128 v[174:177], v152 offset:1024
	ds_read_b128 v[178:181], v152 offset:2048
	ds_read_b128 v[182:185], v152 offset:3072
	s_add_u32 s26, s24, 0xfffc0080
	s_addc_u32 s27, s25, -1
	s_cmp_eq_u32 s51, 12
	s_cselect_b32 s29, s17, s27
	s_cselect_b32 s28, s47, s26
	s_cselect_b32 s27, s15, s50
	s_cselect_b32 s26, s48, s49
	s_add_i32 m0, s23, 0xc000
	ds_read_b128 v[186:189], v153
	ds_read_b128 v[190:193], v153 offset:1024
	ds_read_b128 v[194:197], v153 offset:2048
	ds_read_b128 v[198:201], v153 offset:3072
	ds_read_b128 v[202:205], v153 offset:4096
	ds_read_b128 v[206:209], v153 offset:5120
	ds_read_b128 v[210:213], v153 offset:6144
	ds_read_b128 v[214:217], v153 offset:7168
	global_load_lds_dwordx4 v138, s[24:25]
	s_add_i32 m0, s23, 0xe000
	s_nop 0
	global_load_lds_dwordx4 v140, s[24:25]
	s_waitcnt vmcnt(8)
	s_waitcnt lgkmcnt(0)
	s_barrier
	s_setprio 1
	s_waitcnt lgkmcnt(0)
	v_mfma_f32_16x16x32_bf16 v[126:129], v[154:157], v[186:189], v[126:129]
	v_mfma_f32_16x16x32_bf16 v[122:125], v[162:165], v[186:189], v[122:125]
	v_mfma_f32_16x16x32_bf16 v[110:113], v[154:157], v[194:197], v[110:113]
	v_mfma_f32_16x16x32_bf16 v[106:109], v[162:165], v[194:197], v[106:109]
	v_mfma_f32_16x16x32_bf16 v[94:97], v[154:157], v[202:205], v[94:97]
	v_mfma_f32_16x16x32_bf16 v[90:93], v[162:165], v[202:205], v[90:93]
	v_mfma_f32_16x16x32_bf16 v[78:81], v[154:157], v[210:213], v[78:81]
	v_mfma_f32_16x16x32_bf16 v[74:77], v[162:165], v[210:213], v[74:77]
	v_mfma_f32_16x16x32_bf16 v[126:129], v[158:161], v[190:193], v[126:129]
	v_mfma_f32_16x16x32_bf16 v[122:125], v[166:169], v[190:193], v[122:125]
	v_mfma_f32_16x16x32_bf16 v[110:113], v[158:161], v[198:201], v[110:113]
	v_mfma_f32_16x16x32_bf16 v[106:109], v[166:169], v[198:201], v[106:109]
	v_mfma_f32_16x16x32_bf16 v[94:97], v[158:161], v[206:209], v[94:97]
	v_mfma_f32_16x16x32_bf16 v[90:93], v[166:169], v[206:209], v[90:93]
	v_mfma_f32_16x16x32_bf16 v[78:81], v[158:161], v[214:217], v[78:81]
	v_mfma_f32_16x16x32_bf16 v[74:77], v[166:169], v[214:217], v[74:77]
	s_setprio 0
	s_setprio 1
	v_mfma_f32_16x16x32_bf16 v[118:121], v[170:173], v[186:189], v[118:121]
	v_mfma_f32_16x16x32_bf16 v[114:117], v[178:181], v[186:189], v[114:117]
	v_mfma_f32_16x16x32_bf16 v[102:105], v[170:173], v[194:197], v[102:105]
	v_mfma_f32_16x16x32_bf16 v[98:101], v[178:181], v[194:197], v[98:101]
	v_mfma_f32_16x16x32_bf16 v[86:89], v[170:173], v[202:205], v[86:89]
	v_mfma_f32_16x16x32_bf16 v[82:85], v[178:181], v[202:205], v[82:85]
	v_mfma_f32_16x16x32_bf16 v[70:73], v[170:173], v[210:213], v[70:73]
	v_mfma_f32_16x16x32_bf16 v[66:69], v[178:181], v[210:213], v[66:69]
	v_mfma_f32_16x16x32_bf16 v[118:121], v[174:177], v[190:193], v[118:121]
	v_mfma_f32_16x16x32_bf16 v[114:117], v[182:185], v[190:193], v[114:117]
	v_mfma_f32_16x16x32_bf16 v[102:105], v[174:177], v[198:201], v[102:105]
	v_mfma_f32_16x16x32_bf16 v[98:101], v[182:185], v[198:201], v[98:101]
	v_mfma_f32_16x16x32_bf16 v[86:89], v[174:177], v[206:209], v[86:89]
	v_mfma_f32_16x16x32_bf16 v[82:85], v[182:185], v[206:209], v[82:85]
	v_mfma_f32_16x16x32_bf16 v[70:73], v[174:177], v[214:217], v[70:73]
	v_mfma_f32_16x16x32_bf16 v[66:69], v[182:185], v[214:217], v[66:69]
	s_setprio 0
	s_barrier
	s_add_i32 s52, s44, s34
	v_lshl_add_u64 v[146:147], s[26:27], 0, v[134:135]
	s_mov_b32 m0, s52
	ds_read_b128 v[186:189], v153 offset:16384
	ds_read_b128 v[190:193], v153 offset:17408
	ds_read_b128 v[194:197], v153 offset:18432
	ds_read_b128 v[198:201], v153 offset:19456
	ds_read_b128 v[202:205], v153 offset:20480
	ds_read_b128 v[206:209], v153 offset:21504
	ds_read_b128 v[210:213], v153 offset:22528
	ds_read_b128 v[214:217], v153 offset:23552
	global_load_lds_dwordx4 v134, s[26:27]
	s_add_i32 m0, s52, 0x2000
	s_add_u32 s52, s26, 0x40000
	v_lshl_add_u64 v[218:219], s[26:27], 0, v[130:131]
	s_addc_u32 s53, s27, 0
	s_add_i32 s54, s45, s34
	global_load_lds_dwordx4 v130, s[26:27]
	s_mov_b32 m0, s54
	v_lshl_add_u64 v[222:223], s[28:29], 0, v[132:133]
	global_load_lds_dwordx4 v134, s[52:53]
	s_add_i32 m0, s54, 0x2000
	s_nop 0
	global_load_lds_dwordx4 v130, s[52:53]
	v_lshl_add_u64 v[220:221], s[28:29], 0, v[136:137]
	s_mov_b32 m0, s23
	s_nop 0
	global_load_lds_dwordx4 v136, s[28:29]
	s_mov_b32 m0, s36
	s_nop 0
	global_load_lds_dwordx4 v132, s[28:29]
	s_waitcnt vmcnt(8)
	s_waitcnt lgkmcnt(0)
	s_barrier
	s_setprio 1
	s_waitcnt lgkmcnt(0)
	v_mfma_f32_16x16x32_bf16 v[62:65], v[154:157], v[186:189], v[62:65]
	v_mfma_f32_16x16x32_bf16 v[58:61], v[162:165], v[186:189], v[58:61]
	v_mfma_f32_16x16x32_bf16 v[46:49], v[154:157], v[194:197], v[46:49]
	v_mfma_f32_16x16x32_bf16 v[42:45], v[162:165], v[194:197], v[42:45]
	v_mfma_f32_16x16x32_bf16 v[30:33], v[154:157], v[202:205], v[30:33]
	v_mfma_f32_16x16x32_bf16 v[26:29], v[162:165], v[202:205], v[26:29]
	v_mfma_f32_16x16x32_bf16 v[14:17], v[154:157], v[210:213], v[14:17]
	v_mfma_f32_16x16x32_bf16 v[10:13], v[162:165], v[210:213], v[10:13]
	v_mfma_f32_16x16x32_bf16 v[62:65], v[158:161], v[190:193], v[62:65]
	v_mfma_f32_16x16x32_bf16 v[58:61], v[166:169], v[190:193], v[58:61]
	v_mfma_f32_16x16x32_bf16 v[46:49], v[158:161], v[198:201], v[46:49]
	v_mfma_f32_16x16x32_bf16 v[42:45], v[166:169], v[198:201], v[42:45]
	v_mfma_f32_16x16x32_bf16 v[30:33], v[158:161], v[206:209], v[30:33]
	v_mfma_f32_16x16x32_bf16 v[26:29], v[166:169], v[206:209], v[26:29]
	v_mfma_f32_16x16x32_bf16 v[14:17], v[158:161], v[214:217], v[14:17]
	v_mfma_f32_16x16x32_bf16 v[10:13], v[166:169], v[214:217], v[10:13]
	s_setprio 0
	s_setprio 1
	v_mfma_f32_16x16x32_bf16 v[54:57], v[170:173], v[186:189], v[54:57]
	v_mfma_f32_16x16x32_bf16 v[50:53], v[178:181], v[186:189], v[50:53]
	v_mfma_f32_16x16x32_bf16 v[38:41], v[170:173], v[194:197], v[38:41]
	v_mfma_f32_16x16x32_bf16 v[34:37], v[178:181], v[194:197], v[34:37]
	v_mfma_f32_16x16x32_bf16 v[22:25], v[170:173], v[202:205], v[22:25]
	v_mfma_f32_16x16x32_bf16 v[18:21], v[178:181], v[202:205], v[18:21]
	v_mfma_f32_16x16x32_bf16 v[6:9], v[170:173], v[210:213], v[6:9]
	v_mfma_f32_16x16x32_bf16 v[2:5], v[178:181], v[210:213], v[2:5]
	v_mfma_f32_16x16x32_bf16 v[54:57], v[174:177], v[190:193], v[54:57]
	v_mfma_f32_16x16x32_bf16 v[50:53], v[182:185], v[190:193], v[50:53]
	v_mfma_f32_16x16x32_bf16 v[38:41], v[174:177], v[198:201], v[38:41]
	v_mfma_f32_16x16x32_bf16 v[34:37], v[182:185], v[198:201], v[34:37]
	v_mfma_f32_16x16x32_bf16 v[22:25], v[174:177], v[206:209], v[22:25]
	v_mfma_f32_16x16x32_bf16 v[18:21], v[182:185], v[206:209], v[18:21]
	v_mfma_f32_16x16x32_bf16 v[6:9], v[174:177], v[214:217], v[6:9]
	v_mfma_f32_16x16x32_bf16 v[2:5], v[182:185], v[214:217], v[2:5]
	s_setprio 0
	s_barrier
	s_add_i32 s52, 0, 0x18000
	s_add_i32 s53, 0, 0x1c000
	v_add_u32_e32 v166, s52, v149
	v_add_u32_e32 v182, s53, v149
	ds_read_b128 v[154:157], v166
	ds_read_b128 v[158:161], v166 offset:1024
	ds_read_b128 v[162:165], v166 offset:2048
	ds_read_b128 v[166:169], v166 offset:3072
	ds_read_b128 v[170:173], v182
	ds_read_b128 v[174:177], v182 offset:1024
	ds_read_b128 v[178:181], v182 offset:2048
	ds_read_b128 v[182:185], v182 offset:3072
	s_add_u32 s28, s28, 0x40000
	s_addc_u32 s29, s29, 0
	s_mov_b32 m0, s37
	ds_read_b128 v[186:189], v153 offset:32768
	ds_read_b128 v[190:193], v153 offset:33792
	ds_read_b128 v[194:197], v153 offset:34816
	ds_read_b128 v[198:201], v153 offset:35840
	ds_read_b128 v[202:205], v153 offset:36864
	ds_read_b128 v[206:209], v153 offset:37888
	ds_read_b128 v[210:213], v153 offset:38912
	ds_read_b128 v[214:217], v153 offset:39936
	global_load_lds_dwordx4 v136, s[28:29]
	s_mov_b32 m0, s38
	s_nop 0
	global_load_lds_dwordx4 v132, s[28:29]
	s_waitcnt vmcnt(8)
	s_waitcnt lgkmcnt(0)
	s_barrier
	s_setprio 1
	s_waitcnt lgkmcnt(0)
	v_mfma_f32_16x16x32_bf16 v[126:129], v[154:157], v[186:189], v[126:129]
	v_mfma_f32_16x16x32_bf16 v[122:125], v[162:165], v[186:189], v[122:125]
	v_mfma_f32_16x16x32_bf16 v[110:113], v[154:157], v[194:197], v[110:113]
	v_mfma_f32_16x16x32_bf16 v[106:109], v[162:165], v[194:197], v[106:109]
	v_mfma_f32_16x16x32_bf16 v[94:97], v[154:157], v[202:205], v[94:97]
	v_mfma_f32_16x16x32_bf16 v[90:93], v[162:165], v[202:205], v[90:93]
	v_mfma_f32_16x16x32_bf16 v[78:81], v[154:157], v[210:213], v[78:81]
	v_mfma_f32_16x16x32_bf16 v[74:77], v[162:165], v[210:213], v[74:77]
	v_mfma_f32_16x16x32_bf16 v[126:129], v[158:161], v[190:193], v[126:129]
	v_mfma_f32_16x16x32_bf16 v[122:125], v[166:169], v[190:193], v[122:125]
	v_mfma_f32_16x16x32_bf16 v[110:113], v[158:161], v[198:201], v[110:113]
	v_mfma_f32_16x16x32_bf16 v[106:109], v[166:169], v[198:201], v[106:109]
	v_mfma_f32_16x16x32_bf16 v[94:97], v[158:161], v[206:209], v[94:97]
	v_mfma_f32_16x16x32_bf16 v[90:93], v[166:169], v[206:209], v[90:93]
	v_mfma_f32_16x16x32_bf16 v[78:81], v[158:161], v[214:217], v[78:81]
	v_mfma_f32_16x16x32_bf16 v[74:77], v[166:169], v[214:217], v[74:77]
	s_setprio 0
	s_setprio 1
	v_mfma_f32_16x16x32_bf16 v[118:121], v[170:173], v[186:189], v[118:121]
	v_mfma_f32_16x16x32_bf16 v[114:117], v[178:181], v[186:189], v[114:117]
	v_mfma_f32_16x16x32_bf16 v[102:105], v[170:173], v[194:197], v[102:105]
	v_mfma_f32_16x16x32_bf16 v[98:101], v[178:181], v[194:197], v[98:101]
	v_mfma_f32_16x16x32_bf16 v[86:89], v[170:173], v[202:205], v[86:89]
	v_mfma_f32_16x16x32_bf16 v[82:85], v[178:181], v[202:205], v[82:85]
	v_mfma_f32_16x16x32_bf16 v[70:73], v[170:173], v[210:213], v[70:73]
	v_mfma_f32_16x16x32_bf16 v[66:69], v[178:181], v[210:213], v[66:69]
	v_mfma_f32_16x16x32_bf16 v[118:121], v[174:177], v[190:193], v[118:121]
	v_mfma_f32_16x16x32_bf16 v[114:117], v[182:185], v[190:193], v[114:117]
	v_mfma_f32_16x16x32_bf16 v[102:105], v[174:177], v[198:201], v[102:105]
	v_mfma_f32_16x16x32_bf16 v[98:101], v[182:185], v[198:201], v[98:101]
	v_mfma_f32_16x16x32_bf16 v[86:89], v[174:177], v[206:209], v[86:89]
	v_mfma_f32_16x16x32_bf16 v[82:85], v[182:185], v[206:209], v[82:85]
	v_mfma_f32_16x16x32_bf16 v[70:73], v[174:177], v[214:217], v[70:73]
	v_mfma_f32_16x16x32_bf16 v[66:69], v[182:185], v[214:217], v[66:69]
	s_setprio 0
	s_barrier
	s_add_i32 s28, s52, s34
	v_lshl_add_u64 v[146:147], v[146:147], 0, s[10:11]
	s_mov_b32 m0, s28
	ds_read_b128 v[186:189], v153 offset:49152
	ds_read_b128 v[190:193], v153 offset:50176
	ds_read_b128 v[194:197], v153 offset:51200
	ds_read_b128 v[198:201], v153 offset:52224
	ds_read_b128 v[202:205], v153 offset:53248
	ds_read_b128 v[206:209], v153 offset:54272
	ds_read_b128 v[210:213], v153 offset:55296
	ds_read_b128 v[214:217], v153 offset:56320
	global_load_lds_dwordx4 v[146:147], off
	s_add_i32 m0, s28, 0x2000
	s_add_u32 s26, s26, 0x40080
	v_lshl_add_u64 v[146:147], v[218:219], 0, s[10:11]
	s_addc_u32 s27, s27, 0
	s_add_i32 s28, s53, s34
	global_load_lds_dwordx4 v[146:147], off
	s_mov_b32 m0, s28
	s_nop 0
	global_load_lds_dwordx4 v134, s[26:27]
	s_add_i32 m0, s28, 0x2000
	s_nop 0
	global_load_lds_dwordx4 v130, s[26:27]
	v_lshl_add_u64 v[146:147], v[220:221], 0, s[10:11]
	s_mov_b32 m0, s41
	s_nop 0
	global_load_lds_dwordx4 v[146:147], off
	v_lshl_add_u64 v[146:147], v[222:223], 0, s[10:11]
	s_mov_b32 m0, s42
	s_nop 0
	global_load_lds_dwordx4 v[146:147], off
	s_waitcnt vmcnt(8)
	s_waitcnt lgkmcnt(0)
	s_barrier
	s_setprio 1
	s_waitcnt lgkmcnt(0)
	v_mfma_f32_16x16x32_bf16 v[62:65], v[154:157], v[186:189], v[62:65]
	v_mfma_f32_16x16x32_bf16 v[58:61], v[162:165], v[186:189], v[58:61]
	v_mfma_f32_16x16x32_bf16 v[46:49], v[154:157], v[194:197], v[46:49]
	v_mfma_f32_16x16x32_bf16 v[42:45], v[162:165], v[194:197], v[42:45]
	v_mfma_f32_16x16x32_bf16 v[30:33], v[154:157], v[202:205], v[30:33]
	v_mfma_f32_16x16x32_bf16 v[26:29], v[162:165], v[202:205], v[26:29]
	v_mfma_f32_16x16x32_bf16 v[14:17], v[154:157], v[210:213], v[14:17]
	v_mfma_f32_16x16x32_bf16 v[10:13], v[162:165], v[210:213], v[10:13]
	v_mfma_f32_16x16x32_bf16 v[62:65], v[158:161], v[190:193], v[62:65]
	v_mfma_f32_16x16x32_bf16 v[58:61], v[166:169], v[190:193], v[58:61]
	v_mfma_f32_16x16x32_bf16 v[46:49], v[158:161], v[198:201], v[46:49]
	v_mfma_f32_16x16x32_bf16 v[42:45], v[166:169], v[198:201], v[42:45]
	v_mfma_f32_16x16x32_bf16 v[30:33], v[158:161], v[206:209], v[30:33]
	v_mfma_f32_16x16x32_bf16 v[26:29], v[166:169], v[206:209], v[26:29]
	v_mfma_f32_16x16x32_bf16 v[14:17], v[158:161], v[214:217], v[14:17]
	v_mfma_f32_16x16x32_bf16 v[10:13], v[166:169], v[214:217], v[10:13]
	s_setprio 0
	s_setprio 1
	v_mfma_f32_16x16x32_bf16 v[54:57], v[170:173], v[186:189], v[54:57]
	v_mfma_f32_16x16x32_bf16 v[50:53], v[178:181], v[186:189], v[50:53]
	v_mfma_f32_16x16x32_bf16 v[38:41], v[170:173], v[194:197], v[38:41]
	v_mfma_f32_16x16x32_bf16 v[34:37], v[178:181], v[194:197], v[34:37]
	v_mfma_f32_16x16x32_bf16 v[22:25], v[170:173], v[202:205], v[22:25]
	v_mfma_f32_16x16x32_bf16 v[18:21], v[178:181], v[202:205], v[18:21]
	v_mfma_f32_16x16x32_bf16 v[6:9], v[170:173], v[210:213], v[6:9]
	v_mfma_f32_16x16x32_bf16 v[2:5], v[178:181], v[210:213], v[2:5]
	v_mfma_f32_16x16x32_bf16 v[54:57], v[174:177], v[190:193], v[54:57]
	v_mfma_f32_16x16x32_bf16 v[50:53], v[182:185], v[190:193], v[50:53]
	v_mfma_f32_16x16x32_bf16 v[38:41], v[174:177], v[198:201], v[38:41]
	v_mfma_f32_16x16x32_bf16 v[34:37], v[182:185], v[198:201], v[34:37]
	v_mfma_f32_16x16x32_bf16 v[22:25], v[174:177], v[206:209], v[22:25]
	v_mfma_f32_16x16x32_bf16 v[18:21], v[182:185], v[206:209], v[18:21]
	v_mfma_f32_16x16x32_bf16 v[6:9], v[174:177], v[214:217], v[6:9]
	v_mfma_f32_16x16x32_bf16 v[2:5], v[182:185], v[214:217], v[2:5]
	s_setprio 0
	s_barrier
	s_add_i32 s51, s51, 2
	s_add_u32 s24, s24, 0x100
	s_addc_u32 s25, s25, 0
	s_add_u32 s49, s49, 0x100
	s_addc_u32 s50, s50, 0
	s_cmp_gt_u32 s51, 13
	s_cbranch_scc0 .LBB0_294
	s_and_b64 vcc, exec, s[12:13]
	s_cbranch_vccz .LBB0_297
	s_barrier

.LBB0_391:
	ds_read_b128 v[158:161], v168
	ds_read_b128 v[162:165], v168 offset:1024
	ds_read_b128 v[172:175], v168 offset:2048
	ds_read_b128 v[176:179], v168 offset:3072
	ds_read_b128 v[180:183], v169
	ds_read_b128 v[184:187], v169 offset:1024
	ds_read_b128 v[188:191], v169 offset:2048
	ds_read_b128 v[192:195], v169 offset:3072
	s_add_u32 s22, s20, 0x100
	s_addc_u32 s23, s21, 0
	s_cmp_eq_u32 s50, 40
	s_cselect_b32 s27, s7, s23
	s_cselect_b32 s26, s6, s22
	s_cselect_b32 s25, s19, s49
	s_cselect_b32 s24, s18, s2
	v_lshl_add_u64 v[228:229], s[20:21], 0, v[136:137]
	s_add_i32 m0, s31, 0xc000
	ds_read_b128 v[196:199], v170
	ds_read_b128 v[200:203], v170 offset:1024
	ds_read_b128 v[204:207], v170 offset:2048
	ds_read_b128 v[208:211], v170 offset:3072
	ds_read_b128 v[212:215], v170 offset:4096
	ds_read_b128 v[216:219], v170 offset:5120
	ds_read_b128 v[220:223], v170 offset:6144
	ds_read_b128 v[224:227], v170 offset:7168
	global_load_lds_dwordx4 v[228:229], off
	v_lshl_add_u64 v[228:229], s[20:21], 0, v[138:139]
	s_add_i32 m0, s31, 0xe000
	s_nop 0
	global_load_lds_dwordx4 v[228:229], off
	s_waitcnt vmcnt(8)
	s_waitcnt lgkmcnt(0)
	s_barrier
	s_setprio 1
	s_waitcnt lgkmcnt(0)
	v_mfma_f32_16x16x32_bf16 v[126:129], v[158:161], v[196:199], v[126:129]
	v_mfma_f32_16x16x32_bf16 v[122:125], v[172:175], v[196:199], v[122:125]
	v_mfma_f32_16x16x32_bf16 v[114:117], v[158:161], v[204:207], v[114:117]
	v_mfma_f32_16x16x32_bf16 v[110:113], v[172:175], v[204:207], v[110:113]
	v_mfma_f32_16x16x32_bf16 v[98:101], v[158:161], v[212:215], v[98:101]
	v_mfma_f32_16x16x32_bf16 v[94:97], v[172:175], v[212:215], v[94:97]
	v_mfma_f32_16x16x32_bf16 v[82:85], v[158:161], v[220:223], v[82:85]
	v_mfma_f32_16x16x32_bf16 v[78:81], v[172:175], v[220:223], v[78:81]
	v_mfma_f32_16x16x32_bf16 v[126:129], v[162:165], v[200:203], v[126:129]
	v_mfma_f32_16x16x32_bf16 v[122:125], v[176:179], v[200:203], v[122:125]
	v_mfma_f32_16x16x32_bf16 v[114:117], v[162:165], v[208:211], v[114:117]
	v_mfma_f32_16x16x32_bf16 v[110:113], v[176:179], v[208:211], v[110:113]
	v_mfma_f32_16x16x32_bf16 v[98:101], v[162:165], v[216:219], v[98:101]
	v_mfma_f32_16x16x32_bf16 v[94:97], v[176:179], v[216:219], v[94:97]
	v_mfma_f32_16x16x32_bf16 v[82:85], v[162:165], v[224:227], v[82:85]
	v_mfma_f32_16x16x32_bf16 v[78:81], v[176:179], v[224:227], v[78:81]
	s_setprio 0
	s_setprio 1
	v_mfma_f32_16x16x32_bf16 v[118:121], v[180:183], v[196:199], v[118:121]
	v_mfma_f32_16x16x32_bf16 v[106:109], v[188:191], v[196:199], v[106:109]
	v_mfma_f32_16x16x32_bf16 v[102:105], v[180:183], v[204:207], v[102:105]
	v_mfma_f32_16x16x32_bf16 v[90:93], v[188:191], v[204:207], v[90:93]
	v_mfma_f32_16x16x32_bf16 v[86:89], v[180:183], v[212:215], v[86:89]
	v_mfma_f32_16x16x32_bf16 v[74:77], v[188:191], v[212:215], v[74:77]
	v_mfma_f32_16x16x32_bf16 v[70:73], v[180:183], v[220:223], v[70:73]
	v_mfma_f32_16x16x32_bf16 v[66:69], v[188:191], v[220:223], v[66:69]
	v_mfma_f32_16x16x32_bf16 v[118:121], v[184:187], v[200:203], v[118:121]
	v_mfma_f32_16x16x32_bf16 v[106:109], v[192:195], v[200:203], v[106:109]
	v_mfma_f32_16x16x32_bf16 v[102:105], v[184:187], v[208:211], v[102:105]
	v_mfma_f32_16x16x32_bf16 v[90:93], v[192:195], v[208:211], v[90:93]
	v_mfma_f32_16x16x32_bf16 v[86:89], v[184:187], v[216:219], v[86:89]
	v_mfma_f32_16x16x32_bf16 v[74:77], v[192:195], v[216:219], v[74:77]
	v_mfma_f32_16x16x32_bf16 v[70:73], v[184:187], v[224:227], v[70:73]
	v_mfma_f32_16x16x32_bf16 v[66:69], v[192:195], v[224:227], v[66:69]
	s_setprio 0
	s_barrier
	s_add_i32 s20, s43, s30
	v_lshl_add_u64 v[228:229], s[24:25], 0, v[130:131]
	s_mov_b32 m0, s20
	ds_read_b128 v[196:199], v170 offset:16384
	ds_read_b128 v[200:203], v170 offset:17408
	ds_read_b128 v[204:207], v170 offset:18432
	ds_read_b128 v[208:211], v170 offset:19456
	ds_read_b128 v[212:215], v170 offset:20480
	ds_read_b128 v[216:219], v170 offset:21504
	ds_read_b128 v[220:223], v170 offset:22528
	ds_read_b128 v[224:227], v170 offset:23552
	global_load_lds_dwordx4 v130, s[24:25]
	s_add_i32 m0, s20, 0x2000
	s_add_u32 s20, s24, 0xb0000
	v_lshl_add_u64 v[230:231], s[24:25], 0, v[132:133]
	s_addc_u32 s21, s25, 0
	s_add_i32 s51, s44, s30
	global_load_lds_dwordx4 v132, s[24:25]
	s_mov_b32 m0, s51
	v_lshl_add_u64 v[234:235], s[26:27], 0, v[132:133]
	global_load_lds_dwordx4 v130, s[20:21]
	s_add_i32 m0, s51, 0x2000
	s_nop 0
	global_load_lds_dwordx4 v132, s[20:21]
	v_lshl_add_u64 v[232:233], s[26:27], 0, v[130:131]
	s_mov_b32 m0, s31
	s_nop 0
	global_load_lds_dwordx4 v130, s[26:27]
	s_mov_b32 m0, s33
	s_nop 0
	global_load_lds_dwordx4 v132, s[26:27]
	s_waitcnt vmcnt(8)
	s_waitcnt lgkmcnt(0)
	s_barrier
	s_setprio 1
	s_waitcnt lgkmcnt(0)
	v_mfma_f32_16x16x32_bf16 v[62:65], v[158:161], v[196:199], v[62:65]
	v_mfma_f32_16x16x32_bf16 v[58:61], v[172:175], v[196:199], v[58:61]
	v_mfma_f32_16x16x32_bf16 v[50:53], v[158:161], v[204:207], v[50:53]
	v_mfma_f32_16x16x32_bf16 v[46:49], v[172:175], v[204:207], v[46:49]
	v_mfma_f32_16x16x32_bf16 v[34:37], v[158:161], v[212:215], v[34:37]
	v_mfma_f32_16x16x32_bf16 v[30:33], v[172:175], v[212:215], v[30:33]
	v_mfma_f32_16x16x32_bf16 v[18:21], v[158:161], v[220:223], v[18:21]
	v_mfma_f32_16x16x32_bf16 v[14:17], v[172:175], v[220:223], v[14:17]
	v_mfma_f32_16x16x32_bf16 v[62:65], v[162:165], v[200:203], v[62:65]
	v_mfma_f32_16x16x32_bf16 v[58:61], v[176:179], v[200:203], v[58:61]
	v_mfma_f32_16x16x32_bf16 v[50:53], v[162:165], v[208:211], v[50:53]
	v_mfma_f32_16x16x32_bf16 v[46:49], v[176:179], v[208:211], v[46:49]
	v_mfma_f32_16x16x32_bf16 v[34:37], v[162:165], v[216:219], v[34:37]
	v_mfma_f32_16x16x32_bf16 v[30:33], v[176:179], v[216:219], v[30:33]
	v_mfma_f32_16x16x32_bf16 v[18:21], v[162:165], v[224:227], v[18:21]
	v_mfma_f32_16x16x32_bf16 v[14:17], v[176:179], v[224:227], v[14:17]
	s_setprio 0
	s_setprio 1
	v_mfma_f32_16x16x32_bf16 v[54:57], v[180:183], v[196:199], v[54:57]
	v_mfma_f32_16x16x32_bf16 v[42:45], v[188:191], v[196:199], v[42:45]
	v_mfma_f32_16x16x32_bf16 v[38:41], v[180:183], v[204:207], v[38:41]
	v_mfma_f32_16x16x32_bf16 v[26:29], v[188:191], v[204:207], v[26:29]
	v_mfma_f32_16x16x32_bf16 v[22:25], v[180:183], v[212:215], v[22:25]
	v_mfma_f32_16x16x32_bf16 v[10:13], v[188:191], v[212:215], v[10:13]
	v_mfma_f32_16x16x32_bf16 v[6:9], v[180:183], v[220:223], v[6:9]
	v_mfma_f32_16x16x32_bf16 v[2:5], v[188:191], v[220:223], v[2:5]
	v_mfma_f32_16x16x32_bf16 v[54:57], v[184:187], v[200:203], v[54:57]
	v_mfma_f32_16x16x32_bf16 v[42:45], v[192:195], v[200:203], v[42:45]
	v_mfma_f32_16x16x32_bf16 v[38:41], v[184:187], v[208:211], v[38:41]
	v_mfma_f32_16x16x32_bf16 v[26:29], v[192:195], v[208:211], v[26:29]
	v_mfma_f32_16x16x32_bf16 v[22:25], v[184:187], v[216:219], v[22:25]
	v_mfma_f32_16x16x32_bf16 v[10:13], v[192:195], v[216:219], v[10:13]
	v_mfma_f32_16x16x32_bf16 v[6:9], v[184:187], v[224:227], v[6:9]
	v_mfma_f32_16x16x32_bf16 v[2:5], v[192:195], v[224:227], v[2:5]
	s_setprio 0
	s_barrier
	s_add_i32 s51, 0, 0x18000
	v_add_u32_e32 v171, s51, v166
	s_add_i32 s52, 0, 0x1c000
	ds_read_b128 v[158:161], v171
	ds_read_b128 v[162:165], v171 offset:1024
	ds_read_b128 v[172:175], v171 offset:2048
	ds_read_b128 v[176:179], v171 offset:3072
	v_add_u32_e32 v171, s52, v166
	ds_read_b128 v[180:183], v171
	ds_read_b128 v[184:187], v171 offset:1024
	ds_read_b128 v[188:191], v171 offset:2048
	ds_read_b128 v[192:195], v171 offset:3072
	s_add_u32 s20, s26, 0xb0000
	s_addc_u32 s21, s27, 0
	s_mov_b32 m0, s34
	ds_read_b128 v[196:199], v170 offset:32768
	ds_read_b128 v[200:203], v170 offset:33792
	ds_read_b128 v[204:207], v170 offset:34816
	ds_read_b128 v[208:211], v170 offset:35840
	ds_read_b128 v[212:215], v170 offset:36864
	ds_read_b128 v[216:219], v170 offset:37888
	ds_read_b128 v[220:223], v170 offset:38912
	ds_read_b128 v[224:227], v170 offset:39936
	global_load_lds_dwordx4 v130, s[20:21]
	s_mov_b32 m0, s35
	s_nop 0
	global_load_lds_dwordx4 v132, s[20:21]
	s_waitcnt vmcnt(8)
	s_waitcnt lgkmcnt(0)
	s_barrier
	s_setprio 1
	s_waitcnt lgkmcnt(0)
	v_mfma_f32_16x16x32_bf16 v[126:129], v[158:161], v[196:199], v[126:129]
	v_mfma_f32_16x16x32_bf16 v[122:125], v[172:175], v[196:199], v[122:125]
	v_mfma_f32_16x16x32_bf16 v[114:117], v[158:161], v[204:207], v[114:117]
	v_mfma_f32_16x16x32_bf16 v[110:113], v[172:175], v[204:207], v[110:113]
	v_mfma_f32_16x16x32_bf16 v[98:101], v[158:161], v[212:215], v[98:101]
	v_mfma_f32_16x16x32_bf16 v[94:97], v[172:175], v[212:215], v[94:97]
	v_mfma_f32_16x16x32_bf16 v[82:85], v[158:161], v[220:223], v[82:85]
	v_mfma_f32_16x16x32_bf16 v[78:81], v[172:175], v[220:223], v[78:81]
	v_mfma_f32_16x16x32_bf16 v[126:129], v[162:165], v[200:203], v[126:129]
	v_mfma_f32_16x16x32_bf16 v[122:125], v[176:179], v[200:203], v[122:125]
	v_mfma_f32_16x16x32_bf16 v[114:117], v[162:165], v[208:211], v[114:117]
	v_mfma_f32_16x16x32_bf16 v[110:113], v[176:179], v[208:211], v[110:113]
	v_mfma_f32_16x16x32_bf16 v[98:101], v[162:165], v[216:219], v[98:101]
	v_mfma_f32_16x16x32_bf16 v[94:97], v[176:179], v[216:219], v[94:97]
	v_mfma_f32_16x16x32_bf16 v[82:85], v[162:165], v[224:227], v[82:85]
	v_mfma_f32_16x16x32_bf16 v[78:81], v[176:179], v[224:227], v[78:81]
	s_setprio 0
	s_setprio 1
	v_mfma_f32_16x16x32_bf16 v[118:121], v[180:183], v[196:199], v[118:121]
	v_mfma_f32_16x16x32_bf16 v[106:109], v[188:191], v[196:199], v[106:109]
	v_mfma_f32_16x16x32_bf16 v[102:105], v[180:183], v[204:207], v[102:105]
	v_mfma_f32_16x16x32_bf16 v[90:93], v[188:191], v[204:207], v[90:93]
	v_mfma_f32_16x16x32_bf16 v[86:89], v[180:183], v[212:215], v[86:89]
	v_mfma_f32_16x16x32_bf16 v[74:77], v[188:191], v[212:215], v[74:77]
	v_mfma_f32_16x16x32_bf16 v[70:73], v[180:183], v[220:223], v[70:73]
	v_mfma_f32_16x16x32_bf16 v[66:69], v[188:191], v[220:223], v[66:69]
	v_mfma_f32_16x16x32_bf16 v[118:121], v[184:187], v[200:203], v[118:121]
	v_mfma_f32_16x16x32_bf16 v[106:109], v[192:195], v[200:203], v[106:109]
	v_mfma_f32_16x16x32_bf16 v[102:105], v[184:187], v[208:211], v[102:105]
	v_mfma_f32_16x16x32_bf16 v[90:93], v[192:195], v[208:211], v[90:93]
	v_mfma_f32_16x16x32_bf16 v[86:89], v[184:187], v[216:219], v[86:89]
	v_mfma_f32_16x16x32_bf16 v[74:77], v[192:195], v[216:219], v[74:77]
	v_mfma_f32_16x16x32_bf16 v[70:73], v[184:187], v[224:227], v[70:73]
	v_mfma_f32_16x16x32_bf16 v[66:69], v[192:195], v[224:227], v[66:69]
	s_setprio 0
	s_barrier
	s_add_i32 s20, s51, s30
	v_lshl_add_u64 v[228:229], v[228:229], 0, s[14:15]
	s_mov_b32 m0, s20
	ds_read_b128 v[196:199], v170 offset:49152
	ds_read_b128 v[200:203], v170 offset:50176
	ds_read_b128 v[204:207], v170 offset:51200
	ds_read_b128 v[208:211], v170 offset:52224
	ds_read_b128 v[212:215], v170 offset:53248
	ds_read_b128 v[216:219], v170 offset:54272
	ds_read_b128 v[220:223], v170 offset:55296
	ds_read_b128 v[224:227], v170 offset:56320
	global_load_lds_dwordx4 v[228:229], off
	s_add_i32 m0, s20, 0x2000
	s_add_u32 s20, s24, 0xb0080
	v_lshl_add_u64 v[228:229], v[230:231], 0, s[14:15]
	s_addc_u32 s21, s25, 0
	s_add_i32 s24, s52, s30
	global_load_lds_dwordx4 v[228:229], off
	s_mov_b32 m0, s24
	s_nop 0
	global_load_lds_dwordx4 v130, s[20:21]
	s_add_i32 m0, s24, 0x2000
	s_nop 0
	global_load_lds_dwordx4 v132, s[20:21]
	v_lshl_add_u64 v[228:229], v[232:233], 0, s[14:15]
	s_mov_b32 m0, s39
	s_nop 0
	global_load_lds_dwordx4 v[228:229], off
	v_lshl_add_u64 v[228:229], v[234:235], 0, s[14:15]
	s_mov_b32 m0, s40
	s_nop 0
	global_load_lds_dwordx4 v[228:229], off
	s_waitcnt vmcnt(8)
	s_waitcnt lgkmcnt(0)
	s_barrier
	s_setprio 1
	s_waitcnt lgkmcnt(0)
	v_mfma_f32_16x16x32_bf16 v[62:65], v[158:161], v[196:199], v[62:65]
	v_mfma_f32_16x16x32_bf16 v[58:61], v[172:175], v[196:199], v[58:61]
	v_mfma_f32_16x16x32_bf16 v[50:53], v[158:161], v[204:207], v[50:53]
	v_mfma_f32_16x16x32_bf16 v[46:49], v[172:175], v[204:207], v[46:49]
	v_mfma_f32_16x16x32_bf16 v[34:37], v[158:161], v[212:215], v[34:37]
	v_mfma_f32_16x16x32_bf16 v[30:33], v[172:175], v[212:215], v[30:33]
	v_mfma_f32_16x16x32_bf16 v[18:21], v[158:161], v[220:223], v[18:21]
	v_mfma_f32_16x16x32_bf16 v[14:17], v[172:175], v[220:223], v[14:17]
	v_mfma_f32_16x16x32_bf16 v[62:65], v[162:165], v[200:203], v[62:65]
	v_mfma_f32_16x16x32_bf16 v[58:61], v[176:179], v[200:203], v[58:61]
	v_mfma_f32_16x16x32_bf16 v[50:53], v[162:165], v[208:211], v[50:53]
	v_mfma_f32_16x16x32_bf16 v[46:49], v[176:179], v[208:211], v[46:49]
	v_mfma_f32_16x16x32_bf16 v[34:37], v[162:165], v[216:219], v[34:37]
	v_mfma_f32_16x16x32_bf16 v[30:33], v[176:179], v[216:219], v[30:33]
	v_mfma_f32_16x16x32_bf16 v[18:21], v[162:165], v[224:227], v[18:21]
	v_mfma_f32_16x16x32_bf16 v[14:17], v[176:179], v[224:227], v[14:17]
	s_setprio 0
	s_setprio 1
	v_mfma_f32_16x16x32_bf16 v[54:57], v[180:183], v[196:199], v[54:57]
	v_mfma_f32_16x16x32_bf16 v[42:45], v[188:191], v[196:199], v[42:45]
	v_mfma_f32_16x16x32_bf16 v[38:41], v[180:183], v[204:207], v[38:41]
	v_mfma_f32_16x16x32_bf16 v[26:29], v[188:191], v[204:207], v[26:29]
	v_mfma_f32_16x16x32_bf16 v[22:25], v[180:183], v[212:215], v[22:25]
	v_mfma_f32_16x16x32_bf16 v[10:13], v[188:191], v[212:215], v[10:13]
	v_mfma_f32_16x16x32_bf16 v[6:9], v[180:183], v[220:223], v[6:9]
	v_mfma_f32_16x16x32_bf16 v[2:5], v[188:191], v[220:223], v[2:5]
	v_mfma_f32_16x16x32_bf16 v[54:57], v[184:187], v[200:203], v[54:57]
	v_mfma_f32_16x16x32_bf16 v[42:45], v[192:195], v[200:203], v[42:45]
	v_mfma_f32_16x16x32_bf16 v[38:41], v[184:187], v[208:211], v[38:41]
	v_mfma_f32_16x16x32_bf16 v[26:29], v[192:195], v[208:211], v[26:29]
	v_mfma_f32_16x16x32_bf16 v[22:25], v[184:187], v[216:219], v[22:25]
	v_mfma_f32_16x16x32_bf16 v[10:13], v[192:195], v[216:219], v[10:13]
	v_mfma_f32_16x16x32_bf16 v[6:9], v[184:187], v[224:227], v[6:9]
	v_mfma_f32_16x16x32_bf16 v[2:5], v[192:195], v[224:227], v[2:5]
	s_setprio 0
	s_barrier
	s_add_i32 s50, s50, 2
	s_add_u32 s2, s2, 0x100
	s_addc_u32 s49, s49, 0
	s_cmp_gt_u32 s50, 41
	s_mov_b64 s[20:21], s[22:23]
	s_cbranch_scc0 .LBB0_391
	s_and_b64 vcc, exec, s[16:17]
	s_cbranch_vccz .LBB0_394
	s_barrier

.LBB0_558:
	ds_read_b128 v[146:149], v153
	ds_read_b128 v[156:159], v153 offset:1024
	ds_read_b128 v[160:163], v153 offset:2048
	ds_read_b128 v[164:167], v153 offset:3072
	ds_read_b128 v[168:171], v154
	ds_read_b128 v[172:175], v154 offset:1024
	ds_read_b128 v[176:179], v154 offset:2048
	ds_read_b128 v[180:183], v154 offset:3072
	s_add_u32 s28, s26, 0xfffc0080
	s_addc_u32 s29, s27, -1
	s_cmp_eq_u32 s52, 12
	s_cselect_b32 s31, s2, s29
	s_cselect_b32 s30, s7, s28
	s_cselect_b32 s29, s17, s51
	s_cselect_b32 s28, s19, s25
	s_add_i32 m0, s37, 0xc000
	ds_read_b128 v[184:187], v155
	ds_read_b128 v[188:191], v155 offset:1024
	ds_read_b128 v[192:195], v155 offset:2048
	ds_read_b128 v[196:199], v155 offset:3072
	ds_read_b128 v[200:203], v155 offset:4096
	ds_read_b128 v[204:207], v155 offset:5120
	ds_read_b128 v[208:211], v155 offset:6144
	ds_read_b128 v[212:215], v155 offset:7168
	global_load_lds_dwordx4 v138, s[26:27]
	s_add_i32 m0, s37, 0xe000
	s_nop 0
	global_load_lds_dwordx4 v140, s[26:27]
	s_waitcnt vmcnt(8)
	s_waitcnt lgkmcnt(0)
	s_barrier
	s_setprio 1
	s_waitcnt lgkmcnt(0)
	v_mfma_f32_16x16x32_bf16 v[126:129], v[146:149], v[184:187], v[126:129]
	v_mfma_f32_16x16x32_bf16 v[122:125], v[160:163], v[184:187], v[122:125]
	v_mfma_f32_16x16x32_bf16 v[114:117], v[146:149], v[192:195], v[114:117]
	v_mfma_f32_16x16x32_bf16 v[106:109], v[160:163], v[192:195], v[106:109]
	v_mfma_f32_16x16x32_bf16 v[98:101], v[146:149], v[200:203], v[98:101]
	v_mfma_f32_16x16x32_bf16 v[90:93], v[160:163], v[200:203], v[90:93]
	v_mfma_f32_16x16x32_bf16 v[82:85], v[146:149], v[208:211], v[82:85]
	v_mfma_f32_16x16x32_bf16 v[74:77], v[160:163], v[208:211], v[74:77]
	v_mfma_f32_16x16x32_bf16 v[126:129], v[156:159], v[188:191], v[126:129]
	v_mfma_f32_16x16x32_bf16 v[122:125], v[164:167], v[188:191], v[122:125]
	v_mfma_f32_16x16x32_bf16 v[114:117], v[156:159], v[196:199], v[114:117]
	v_mfma_f32_16x16x32_bf16 v[106:109], v[164:167], v[196:199], v[106:109]
	v_mfma_f32_16x16x32_bf16 v[98:101], v[156:159], v[204:207], v[98:101]
	v_mfma_f32_16x16x32_bf16 v[90:93], v[164:167], v[204:207], v[90:93]
	v_mfma_f32_16x16x32_bf16 v[82:85], v[156:159], v[212:215], v[82:85]
	v_mfma_f32_16x16x32_bf16 v[74:77], v[164:167], v[212:215], v[74:77]
	s_setprio 0
	s_setprio 1
	v_mfma_f32_16x16x32_bf16 v[118:121], v[168:171], v[184:187], v[118:121]
	v_mfma_f32_16x16x32_bf16 v[110:113], v[176:179], v[184:187], v[110:113]
	v_mfma_f32_16x16x32_bf16 v[102:105], v[168:171], v[192:195], v[102:105]
	v_mfma_f32_16x16x32_bf16 v[94:97], v[176:179], v[192:195], v[94:97]
	v_mfma_f32_16x16x32_bf16 v[86:89], v[168:171], v[200:203], v[86:89]
	v_mfma_f32_16x16x32_bf16 v[78:81], v[176:179], v[200:203], v[78:81]
	v_mfma_f32_16x16x32_bf16 v[70:73], v[168:171], v[208:211], v[70:73]
	v_mfma_f32_16x16x32_bf16 v[66:69], v[176:179], v[208:211], v[66:69]
	v_mfma_f32_16x16x32_bf16 v[118:121], v[172:175], v[188:191], v[118:121]
	v_mfma_f32_16x16x32_bf16 v[110:113], v[180:183], v[188:191], v[110:113]
	v_mfma_f32_16x16x32_bf16 v[102:105], v[172:175], v[196:199], v[102:105]
	v_mfma_f32_16x16x32_bf16 v[94:97], v[180:183], v[196:199], v[94:97]
	v_mfma_f32_16x16x32_bf16 v[86:89], v[172:175], v[204:207], v[86:89]
	v_mfma_f32_16x16x32_bf16 v[78:81], v[180:183], v[204:207], v[78:81]
	v_mfma_f32_16x16x32_bf16 v[70:73], v[172:175], v[212:215], v[70:73]
	v_mfma_f32_16x16x32_bf16 v[66:69], v[180:183], v[212:215], v[66:69]
	s_setprio 0
	s_barrier
	s_add_i32 s53, s47, s36
	v_lshl_add_u64 v[216:217], s[28:29], 0, v[132:133]
	s_mov_b32 m0, s53
	ds_read_b128 v[184:187], v155 offset:16384
	ds_read_b128 v[188:191], v155 offset:17408
	ds_read_b128 v[192:195], v155 offset:18432
	ds_read_b128 v[196:199], v155 offset:19456
	ds_read_b128 v[200:203], v155 offset:20480
	ds_read_b128 v[204:207], v155 offset:21504
	ds_read_b128 v[208:211], v155 offset:22528
	ds_read_b128 v[212:215], v155 offset:23552
	global_load_lds_dwordx4 v132, s[28:29]
	s_add_i32 m0, s53, 0x2000
	s_add_u32 s54, s28, 0x40000
	v_lshl_add_u64 v[218:219], s[28:29], 0, v[136:137]
	s_addc_u32 s55, s29, 0
	s_add_i32 s53, s48, s36
	global_load_lds_dwordx4 v136, s[28:29]
	s_mov_b32 m0, s53
	v_lshl_add_u64 v[222:223], s[30:31], 0, v[134:135]
	global_load_lds_dwordx4 v132, s[54:55]
	s_add_i32 m0, s53, 0x2000
	s_nop 0
	global_load_lds_dwordx4 v136, s[54:55]
	v_lshl_add_u64 v[220:221], s[30:31], 0, v[130:131]
	s_mov_b32 m0, s37
	s_nop 0
	global_load_lds_dwordx4 v130, s[30:31]
	s_mov_b32 m0, s38
	s_nop 0
	global_load_lds_dwordx4 v134, s[30:31]
	s_waitcnt vmcnt(8)
	s_waitcnt lgkmcnt(0)
	s_barrier
	s_setprio 1
	s_waitcnt lgkmcnt(0)
	v_mfma_f32_16x16x32_bf16 v[62:65], v[146:149], v[184:187], v[62:65]
	v_mfma_f32_16x16x32_bf16 v[58:61], v[160:163], v[184:187], v[58:61]
	v_mfma_f32_16x16x32_bf16 v[50:53], v[146:149], v[192:195], v[50:53]
	v_mfma_f32_16x16x32_bf16 v[42:45], v[160:163], v[192:195], v[42:45]
	v_mfma_f32_16x16x32_bf16 v[34:37], v[146:149], v[200:203], v[34:37]
	v_mfma_f32_16x16x32_bf16 v[26:29], v[160:163], v[200:203], v[26:29]
	v_mfma_f32_16x16x32_bf16 v[18:21], v[146:149], v[208:211], v[18:21]
	v_mfma_f32_16x16x32_bf16 v[10:13], v[160:163], v[208:211], v[10:13]
	v_mfma_f32_16x16x32_bf16 v[62:65], v[156:159], v[188:191], v[62:65]
	v_mfma_f32_16x16x32_bf16 v[58:61], v[164:167], v[188:191], v[58:61]
	v_mfma_f32_16x16x32_bf16 v[50:53], v[156:159], v[196:199], v[50:53]
	v_mfma_f32_16x16x32_bf16 v[42:45], v[164:167], v[196:199], v[42:45]
	v_mfma_f32_16x16x32_bf16 v[34:37], v[156:159], v[204:207], v[34:37]
	v_mfma_f32_16x16x32_bf16 v[26:29], v[164:167], v[204:207], v[26:29]
	v_mfma_f32_16x16x32_bf16 v[18:21], v[156:159], v[212:215], v[18:21]
	v_mfma_f32_16x16x32_bf16 v[10:13], v[164:167], v[212:215], v[10:13]
	s_setprio 0
	s_setprio 1
	v_mfma_f32_16x16x32_bf16 v[54:57], v[168:171], v[184:187], v[54:57]
	v_mfma_f32_16x16x32_bf16 v[46:49], v[176:179], v[184:187], v[46:49]
	v_mfma_f32_16x16x32_bf16 v[38:41], v[168:171], v[192:195], v[38:41]
	v_mfma_f32_16x16x32_bf16 v[30:33], v[176:179], v[192:195], v[30:33]
	v_mfma_f32_16x16x32_bf16 v[22:25], v[168:171], v[200:203], v[22:25]
	v_mfma_f32_16x16x32_bf16 v[14:17], v[176:179], v[200:203], v[14:17]
	v_mfma_f32_16x16x32_bf16 v[6:9], v[168:171], v[208:211], v[6:9]
	v_mfma_f32_16x16x32_bf16 v[2:5], v[176:179], v[208:211], v[2:5]
	v_mfma_f32_16x16x32_bf16 v[54:57], v[172:175], v[188:191], v[54:57]
	v_mfma_f32_16x16x32_bf16 v[46:49], v[180:183], v[188:191], v[46:49]
	v_mfma_f32_16x16x32_bf16 v[38:41], v[172:175], v[196:199], v[38:41]
	v_mfma_f32_16x16x32_bf16 v[30:33], v[180:183], v[196:199], v[30:33]
	v_mfma_f32_16x16x32_bf16 v[22:25], v[172:175], v[204:207], v[22:25]
	v_mfma_f32_16x16x32_bf16 v[14:17], v[180:183], v[204:207], v[14:17]
	v_mfma_f32_16x16x32_bf16 v[6:9], v[172:175], v[212:215], v[6:9]
	v_mfma_f32_16x16x32_bf16 v[2:5], v[180:183], v[212:215], v[2:5]
	s_setprio 0
	s_barrier
	s_add_i32 s53, 0, 0x18000
	s_add_i32 s54, 0, 0x1c000
	v_add_u32_e32 v164, s53, v151
	v_add_u32_e32 v180, s54, v151
	ds_read_b128 v[146:149], v164
	ds_read_b128 v[156:159], v164 offset:1024
	ds_read_b128 v[160:163], v164 offset:2048
	ds_read_b128 v[164:167], v164 offset:3072
	ds_read_b128 v[168:171], v180
	ds_read_b128 v[172:175], v180 offset:1024
	ds_read_b128 v[176:179], v180 offset:2048
	ds_read_b128 v[180:183], v180 offset:3072
	s_add_u32 s30, s30, 0x40000
	s_addc_u32 s31, s31, 0
	s_mov_b32 m0, s39
	ds_read_b128 v[184:187], v155 offset:32768
	ds_read_b128 v[188:191], v155 offset:33792
	ds_read_b128 v[192:195], v155 offset:34816
	ds_read_b128 v[196:199], v155 offset:35840
	ds_read_b128 v[200:203], v155 offset:36864
	ds_read_b128 v[204:207], v155 offset:37888
	ds_read_b128 v[208:211], v155 offset:38912
	ds_read_b128 v[212:215], v155 offset:39936
	global_load_lds_dwordx4 v130, s[30:31]
	s_mov_b32 m0, s40
	s_nop 0
	global_load_lds_dwordx4 v134, s[30:31]
	s_waitcnt vmcnt(8)
	s_waitcnt lgkmcnt(0)
	s_barrier
	s_setprio 1
	s_waitcnt lgkmcnt(0)
	v_mfma_f32_16x16x32_bf16 v[126:129], v[146:149], v[184:187], v[126:129]
	v_mfma_f32_16x16x32_bf16 v[122:125], v[160:163], v[184:187], v[122:125]
	v_mfma_f32_16x16x32_bf16 v[114:117], v[146:149], v[192:195], v[114:117]
	v_mfma_f32_16x16x32_bf16 v[106:109], v[160:163], v[192:195], v[106:109]
	v_mfma_f32_16x16x32_bf16 v[98:101], v[146:149], v[200:203], v[98:101]
	v_mfma_f32_16x16x32_bf16 v[90:93], v[160:163], v[200:203], v[90:93]
	v_mfma_f32_16x16x32_bf16 v[82:85], v[146:149], v[208:211], v[82:85]
	v_mfma_f32_16x16x32_bf16 v[74:77], v[160:163], v[208:211], v[74:77]
	v_mfma_f32_16x16x32_bf16 v[126:129], v[156:159], v[188:191], v[126:129]
	v_mfma_f32_16x16x32_bf16 v[122:125], v[164:167], v[188:191], v[122:125]
	v_mfma_f32_16x16x32_bf16 v[114:117], v[156:159], v[196:199], v[114:117]
	v_mfma_f32_16x16x32_bf16 v[106:109], v[164:167], v[196:199], v[106:109]
	v_mfma_f32_16x16x32_bf16 v[98:101], v[156:159], v[204:207], v[98:101]
	v_mfma_f32_16x16x32_bf16 v[90:93], v[164:167], v[204:207], v[90:93]
	v_mfma_f32_16x16x32_bf16 v[82:85], v[156:159], v[212:215], v[82:85]
	v_mfma_f32_16x16x32_bf16 v[74:77], v[164:167], v[212:215], v[74:77]
	s_setprio 0
	s_setprio 1
	v_mfma_f32_16x16x32_bf16 v[118:121], v[168:171], v[184:187], v[118:121]
	v_mfma_f32_16x16x32_bf16 v[110:113], v[176:179], v[184:187], v[110:113]
	v_mfma_f32_16x16x32_bf16 v[102:105], v[168:171], v[192:195], v[102:105]
	v_mfma_f32_16x16x32_bf16 v[94:97], v[176:179], v[192:195], v[94:97]
	v_mfma_f32_16x16x32_bf16 v[86:89], v[168:171], v[200:203], v[86:89]
	v_mfma_f32_16x16x32_bf16 v[78:81], v[176:179], v[200:203], v[78:81]
	v_mfma_f32_16x16x32_bf16 v[70:73], v[168:171], v[208:211], v[70:73]
	v_mfma_f32_16x16x32_bf16 v[66:69], v[176:179], v[208:211], v[66:69]
	v_mfma_f32_16x16x32_bf16 v[118:121], v[172:175], v[188:191], v[118:121]
	v_mfma_f32_16x16x32_bf16 v[110:113], v[180:183], v[188:191], v[110:113]
	v_mfma_f32_16x16x32_bf16 v[102:105], v[172:175], v[196:199], v[102:105]
	v_mfma_f32_16x16x32_bf16 v[94:97], v[180:183], v[196:199], v[94:97]
	v_mfma_f32_16x16x32_bf16 v[86:89], v[172:175], v[204:207], v[86:89]
	v_mfma_f32_16x16x32_bf16 v[78:81], v[180:183], v[204:207], v[78:81]
	v_mfma_f32_16x16x32_bf16 v[70:73], v[172:175], v[212:215], v[70:73]
	v_mfma_f32_16x16x32_bf16 v[66:69], v[180:183], v[212:215], v[66:69]
	s_setprio 0
	s_barrier
	s_add_i32 s30, s53, s36
	v_lshl_add_u64 v[216:217], v[216:217], 0, s[12:13]
	s_mov_b32 m0, s30
	ds_read_b128 v[184:187], v155 offset:49152
	ds_read_b128 v[188:191], v155 offset:50176
	ds_read_b128 v[192:195], v155 offset:51200
	ds_read_b128 v[196:199], v155 offset:52224
	ds_read_b128 v[200:203], v155 offset:53248
	ds_read_b128 v[204:207], v155 offset:54272
	ds_read_b128 v[208:211], v155 offset:55296
	ds_read_b128 v[212:215], v155 offset:56320
	global_load_lds_dwordx4 v[216:217], off
	s_add_i32 m0, s30, 0x2000
	s_add_u32 s28, s28, 0x40080
	v_lshl_add_u64 v[216:217], v[218:219], 0, s[12:13]
	s_addc_u32 s29, s29, 0
	s_add_i32 s30, s54, s36
	global_load_lds_dwordx4 v[216:217], off
	s_mov_b32 m0, s30
	s_nop 0
	global_load_lds_dwordx4 v132, s[28:29]
	s_add_i32 m0, s30, 0x2000
	s_nop 0
	global_load_lds_dwordx4 v136, s[28:29]
	v_lshl_add_u64 v[216:217], v[220:221], 0, s[12:13]
	s_mov_b32 m0, s42
	s_nop 0
	global_load_lds_dwordx4 v[216:217], off
	v_lshl_add_u64 v[216:217], v[222:223], 0, s[12:13]
	s_mov_b32 m0, s43
	s_nop 0
	global_load_lds_dwordx4 v[216:217], off
	s_waitcnt vmcnt(8)
	s_waitcnt lgkmcnt(0)
	s_barrier
	s_setprio 1
	s_waitcnt lgkmcnt(0)
	v_mfma_f32_16x16x32_bf16 v[62:65], v[146:149], v[184:187], v[62:65]
	v_mfma_f32_16x16x32_bf16 v[58:61], v[160:163], v[184:187], v[58:61]
	v_mfma_f32_16x16x32_bf16 v[50:53], v[146:149], v[192:195], v[50:53]
	v_mfma_f32_16x16x32_bf16 v[42:45], v[160:163], v[192:195], v[42:45]
	v_mfma_f32_16x16x32_bf16 v[34:37], v[146:149], v[200:203], v[34:37]
	v_mfma_f32_16x16x32_bf16 v[26:29], v[160:163], v[200:203], v[26:29]
	v_mfma_f32_16x16x32_bf16 v[18:21], v[146:149], v[208:211], v[18:21]
	v_mfma_f32_16x16x32_bf16 v[10:13], v[160:163], v[208:211], v[10:13]
	v_mfma_f32_16x16x32_bf16 v[62:65], v[156:159], v[188:191], v[62:65]
	v_mfma_f32_16x16x32_bf16 v[58:61], v[164:167], v[188:191], v[58:61]
	v_mfma_f32_16x16x32_bf16 v[50:53], v[156:159], v[196:199], v[50:53]
	v_mfma_f32_16x16x32_bf16 v[42:45], v[164:167], v[196:199], v[42:45]
	v_mfma_f32_16x16x32_bf16 v[34:37], v[156:159], v[204:207], v[34:37]
	v_mfma_f32_16x16x32_bf16 v[26:29], v[164:167], v[204:207], v[26:29]
	v_mfma_f32_16x16x32_bf16 v[18:21], v[156:159], v[212:215], v[18:21]
	v_mfma_f32_16x16x32_bf16 v[10:13], v[164:167], v[212:215], v[10:13]
	s_setprio 0
	s_setprio 1
	v_mfma_f32_16x16x32_bf16 v[54:57], v[168:171], v[184:187], v[54:57]
	v_mfma_f32_16x16x32_bf16 v[46:49], v[176:179], v[184:187], v[46:49]
	v_mfma_f32_16x16x32_bf16 v[38:41], v[168:171], v[192:195], v[38:41]
	v_mfma_f32_16x16x32_bf16 v[30:33], v[176:179], v[192:195], v[30:33]
	v_mfma_f32_16x16x32_bf16 v[22:25], v[168:171], v[200:203], v[22:25]
	v_mfma_f32_16x16x32_bf16 v[14:17], v[176:179], v[200:203], v[14:17]
	v_mfma_f32_16x16x32_bf16 v[6:9], v[168:171], v[208:211], v[6:9]
	v_mfma_f32_16x16x32_bf16 v[2:5], v[176:179], v[208:211], v[2:5]
	v_mfma_f32_16x16x32_bf16 v[54:57], v[172:175], v[188:191], v[54:57]
	v_mfma_f32_16x16x32_bf16 v[46:49], v[180:183], v[188:191], v[46:49]
	v_mfma_f32_16x16x32_bf16 v[38:41], v[172:175], v[196:199], v[38:41]
	v_mfma_f32_16x16x32_bf16 v[30:33], v[180:183], v[196:199], v[30:33]
	v_mfma_f32_16x16x32_bf16 v[22:25], v[172:175], v[204:207], v[22:25]
	v_mfma_f32_16x16x32_bf16 v[14:17], v[180:183], v[204:207], v[14:17]
	v_mfma_f32_16x16x32_bf16 v[6:9], v[172:175], v[212:215], v[6:9]
	v_mfma_f32_16x16x32_bf16 v[2:5], v[180:183], v[212:215], v[2:5]
	s_setprio 0
	s_barrier
	s_add_i32 s52, s52, 2
	s_add_u32 s26, s26, 0x100
	s_addc_u32 s27, s27, 0
	s_add_u32 s25, s25, 0x100
	s_addc_u32 s51, s51, 0
	s_cmp_gt_u32 s52, 13
	s_cbranch_scc0 .LBB0_558
	s_and_b64 vcc, exec, s[14:15]
	s_cbranch_vccz .LBB0_561
	s_barrier

.LBB0_1101:
	ds_read_b128 v[58:61], v178
	ds_read_b128 v[110:113], v178 offset:1024
	ds_read_b128 v[114:117], v178 offset:2048
	ds_read_b128 v[122:125], v178 offset:3072
	ds_read_b128 v[182:185], v179
	ds_read_b128 v[186:189], v179 offset:1024
	ds_read_b128 v[190:193], v179 offset:2048
	ds_read_b128 v[194:197], v179 offset:3072
	s_add_u32 s28, s26, 0x100
	s_addc_u32 s29, s27, 0
	s_cmp_eq_u32 s54, 12
	s_cselect_b32 s35, s2, s29
	s_cselect_b32 s34, s19, s28
	s_cselect_b32 s31, s17, s53
	s_cselect_b32 s30, s51, s52
	v_lshl_add_u64 v[174:175], s[26:27], 0, v[166:167]
	s_add_i32 m0, s38, 0xc000
	ds_read_b128 v[198:201], v180
	ds_read_b128 v[202:205], v180 offset:1024
	ds_read_b128 v[206:209], v180 offset:2048
	ds_read_b128 v[210:213], v180 offset:3072
	ds_read_b128 v[214:217], v180 offset:4096
	ds_read_b128 v[218:221], v180 offset:5120
	ds_read_b128 v[222:225], v180 offset:6144
	ds_read_b128 v[226:229], v180 offset:7168
	global_load_lds_dwordx4 v[174:175], off
	v_lshl_add_u64 v[174:175], s[26:27], 0, v[168:169]
	s_add_i32 m0, s38, 0xe000
	s_nop 0
	global_load_lds_dwordx4 v[174:175], off
	s_waitcnt vmcnt(8)
	s_waitcnt lgkmcnt(0)
	s_barrier
	s_setprio 1
	s_waitcnt lgkmcnt(0)
	v_mfma_f32_16x16x32_bf16 v[142:145], v[58:61], v[198:201], v[142:145]
	v_mfma_f32_16x16x32_bf16 v[138:141], v[114:117], v[198:201], v[138:141]
	v_mfma_f32_16x16x32_bf16 v[130:133], v[58:61], v[206:209], v[130:133]
	v_mfma_f32_16x16x32_bf16 v[118:121], v[114:117], v[206:209], v[118:121]
	v_mfma_f32_16x16x32_bf16 v[102:105], v[58:61], v[214:217], v[102:105]
	v_mfma_f32_16x16x32_bf16 v[94:97], v[114:117], v[214:217], v[94:97]
	v_mfma_f32_16x16x32_bf16 v[86:89], v[58:61], v[222:225], v[86:89]
	v_mfma_f32_16x16x32_bf16 v[78:81], v[114:117], v[222:225], v[78:81]
	v_mfma_f32_16x16x32_bf16 v[142:145], v[110:113], v[202:205], v[142:145]
	v_mfma_f32_16x16x32_bf16 v[138:141], v[122:125], v[202:205], v[138:141]
	v_mfma_f32_16x16x32_bf16 v[130:133], v[110:113], v[210:213], v[130:133]
	v_mfma_f32_16x16x32_bf16 v[118:121], v[122:125], v[210:213], v[118:121]
	v_mfma_f32_16x16x32_bf16 v[102:105], v[110:113], v[218:221], v[102:105]
	v_mfma_f32_16x16x32_bf16 v[94:97], v[122:125], v[218:221], v[94:97]
	v_mfma_f32_16x16x32_bf16 v[86:89], v[110:113], v[226:229], v[86:89]
	v_mfma_f32_16x16x32_bf16 v[78:81], v[122:125], v[226:229], v[78:81]
	s_setprio 0
	s_setprio 1
	v_mfma_f32_16x16x32_bf16 v[134:137], v[182:185], v[198:201], v[134:137]
	v_mfma_f32_16x16x32_bf16 v[126:129], v[190:193], v[198:201], v[126:129]
	v_mfma_f32_16x16x32_bf16 v[106:109], v[182:185], v[206:209], v[106:109]
	v_mfma_f32_16x16x32_bf16 v[98:101], v[190:193], v[206:209], v[98:101]
	v_mfma_f32_16x16x32_bf16 v[90:93], v[182:185], v[214:217], v[90:93]
	v_mfma_f32_16x16x32_bf16 v[82:85], v[190:193], v[214:217], v[82:85]
	v_mfma_f32_16x16x32_bf16 v[74:77], v[182:185], v[222:225], v[74:77]
	v_mfma_f32_16x16x32_bf16 v[70:73], v[190:193], v[222:225], v[70:73]
	v_mfma_f32_16x16x32_bf16 v[134:137], v[186:189], v[202:205], v[134:137]
	v_mfma_f32_16x16x32_bf16 v[126:129], v[194:197], v[202:205], v[126:129]
	v_mfma_f32_16x16x32_bf16 v[106:109], v[186:189], v[210:213], v[106:109]
	v_mfma_f32_16x16x32_bf16 v[98:101], v[194:197], v[210:213], v[98:101]
	v_mfma_f32_16x16x32_bf16 v[90:93], v[186:189], v[218:221], v[90:93]
	v_mfma_f32_16x16x32_bf16 v[82:85], v[194:197], v[218:221], v[82:85]
	v_mfma_f32_16x16x32_bf16 v[74:77], v[186:189], v[226:229], v[74:77]
	v_mfma_f32_16x16x32_bf16 v[70:73], v[194:197], v[226:229], v[70:73]
	s_setprio 0
	s_barrier
	s_add_i32 s26, s49, s37
	v_lshl_add_u64 v[174:175], s[30:31], 0, v[146:147]
	s_mov_b32 m0, s26
	ds_read_b128 v[198:201], v180 offset:16384
	ds_read_b128 v[202:205], v180 offset:17408
	ds_read_b128 v[206:209], v180 offset:18432
	ds_read_b128 v[210:213], v180 offset:19456
	ds_read_b128 v[214:217], v180 offset:20480
	ds_read_b128 v[218:221], v180 offset:21504
	ds_read_b128 v[222:225], v180 offset:22528
	ds_read_b128 v[226:229], v180 offset:23552
	global_load_lds_dwordx4 v146, s[30:31]
	s_add_i32 m0, s26, 0x2000
	s_add_u32 s26, s30, 0x40000
	v_lshl_add_u64 v[230:231], s[30:31], 0, v[148:149]
	s_addc_u32 s27, s31, 0
	s_add_i32 s55, s50, s37
	global_load_lds_dwordx4 v148, s[30:31]
	s_mov_b32 m0, s55
	v_lshl_add_u64 v[234:235], s[34:35], 0, v[148:149]
	global_load_lds_dwordx4 v146, s[26:27]
	s_add_i32 m0, s55, 0x2000
	s_nop 0
	global_load_lds_dwordx4 v148, s[26:27]
	v_lshl_add_u64 v[232:233], s[34:35], 0, v[146:147]
	s_mov_b32 m0, s38
	s_nop 0
	global_load_lds_dwordx4 v146, s[34:35]
	s_mov_b32 m0, s39
	s_nop 0
	global_load_lds_dwordx4 v148, s[34:35]
	s_waitcnt vmcnt(8)
	s_waitcnt lgkmcnt(0)
	s_barrier
	s_setprio 1
	s_waitcnt lgkmcnt(0)
	v_mfma_f32_16x16x32_bf16 v[66:69], v[58:61], v[198:201], v[66:69]
	v_mfma_f32_16x16x32_bf16 v[62:65], v[114:117], v[198:201], v[62:65]
	v_mfma_f32_16x16x32_bf16 v[46:49], v[58:61], v[206:209], v[46:49]
	v_mfma_f32_16x16x32_bf16 v[42:45], v[114:117], v[206:209], v[42:45]
	v_mfma_f32_16x16x32_bf16 v[30:33], v[58:61], v[214:217], v[30:33]
	v_mfma_f32_16x16x32_bf16 v[26:29], v[114:117], v[214:217], v[26:29]
	v_mfma_f32_16x16x32_bf16 v[14:17], v[58:61], v[222:225], v[14:17]
	v_mfma_f32_16x16x32_bf16 v[10:13], v[114:117], v[222:225], v[10:13]
	v_mfma_f32_16x16x32_bf16 v[66:69], v[110:113], v[202:205], v[66:69]
	v_mfma_f32_16x16x32_bf16 v[62:65], v[122:125], v[202:205], v[62:65]
	v_mfma_f32_16x16x32_bf16 v[46:49], v[110:113], v[210:213], v[46:49]
	v_mfma_f32_16x16x32_bf16 v[42:45], v[122:125], v[210:213], v[42:45]
	v_mfma_f32_16x16x32_bf16 v[30:33], v[110:113], v[218:221], v[30:33]
	v_mfma_f32_16x16x32_bf16 v[26:29], v[122:125], v[218:221], v[26:29]
	v_mfma_f32_16x16x32_bf16 v[14:17], v[110:113], v[226:229], v[14:17]
	v_mfma_f32_16x16x32_bf16 v[10:13], v[122:125], v[226:229], v[10:13]
	s_setprio 0
	s_setprio 1
	v_mfma_f32_16x16x32_bf16 v[54:57], v[182:185], v[198:201], v[54:57]
	v_mfma_f32_16x16x32_bf16 v[50:53], v[190:193], v[198:201], v[50:53]
	v_mfma_f32_16x16x32_bf16 v[38:41], v[182:185], v[206:209], v[38:41]
	v_mfma_f32_16x16x32_bf16 v[34:37], v[190:193], v[206:209], v[34:37]
	v_mfma_f32_16x16x32_bf16 v[22:25], v[182:185], v[214:217], v[22:25]
	v_mfma_f32_16x16x32_bf16 v[18:21], v[190:193], v[214:217], v[18:21]
	v_mfma_f32_16x16x32_bf16 v[6:9], v[182:185], v[222:225], v[6:9]
	v_mfma_f32_16x16x32_bf16 v[2:5], v[190:193], v[222:225], v[2:5]
	v_mfma_f32_16x16x32_bf16 v[54:57], v[186:189], v[202:205], v[54:57]
	v_mfma_f32_16x16x32_bf16 v[50:53], v[194:197], v[202:205], v[50:53]
	v_mfma_f32_16x16x32_bf16 v[38:41], v[186:189], v[210:213], v[38:41]
	v_mfma_f32_16x16x32_bf16 v[34:37], v[194:197], v[210:213], v[34:37]
	v_mfma_f32_16x16x32_bf16 v[22:25], v[186:189], v[218:221], v[22:25]
	v_mfma_f32_16x16x32_bf16 v[18:21], v[194:197], v[218:221], v[18:21]
	v_mfma_f32_16x16x32_bf16 v[6:9], v[186:189], v[226:229], v[6:9]
	v_mfma_f32_16x16x32_bf16 v[2:5], v[194:197], v[226:229], v[2:5]
	s_setprio 0
	s_barrier
	s_add_i32 s55, 0, 0x18000
	s_add_i32 s56, 0, 0x1c000
	v_add_u32_e32 v122, s55, v176
	v_add_u32_e32 v181, s56, v176
	ds_read_b128 v[58:61], v122
	ds_read_b128 v[110:113], v122 offset:1024
	ds_read_b128 v[114:117], v122 offset:2048
	ds_read_b128 v[122:125], v122 offset:3072
	ds_read_b128 v[182:185], v181
	ds_read_b128 v[186:189], v181 offset:1024
	ds_read_b128 v[190:193], v181 offset:2048
	ds_read_b128 v[194:197], v181 offset:3072
	s_add_u32 s26, s34, 0x40000
	s_addc_u32 s27, s35, 0
	s_mov_b32 m0, s40
	ds_read_b128 v[198:201], v180 offset:32768
	ds_read_b128 v[202:205], v180 offset:33792
	ds_read_b128 v[206:209], v180 offset:34816
	ds_read_b128 v[210:213], v180 offset:35840
	ds_read_b128 v[214:217], v180 offset:36864
	ds_read_b128 v[218:221], v180 offset:37888
	ds_read_b128 v[222:225], v180 offset:38912
	ds_read_b128 v[226:229], v180 offset:39936
	global_load_lds_dwordx4 v146, s[26:27]
	s_mov_b32 m0, s41
	s_nop 0
	global_load_lds_dwordx4 v148, s[26:27]
	s_waitcnt vmcnt(8)
	s_waitcnt lgkmcnt(0)
	s_barrier
	s_setprio 1
	s_waitcnt lgkmcnt(0)
	v_mfma_f32_16x16x32_bf16 v[142:145], v[58:61], v[198:201], v[142:145]
	v_mfma_f32_16x16x32_bf16 v[138:141], v[114:117], v[198:201], v[138:141]
	v_mfma_f32_16x16x32_bf16 v[130:133], v[58:61], v[206:209], v[130:133]
	v_mfma_f32_16x16x32_bf16 v[118:121], v[114:117], v[206:209], v[118:121]
	v_mfma_f32_16x16x32_bf16 v[102:105], v[58:61], v[214:217], v[102:105]
	v_mfma_f32_16x16x32_bf16 v[94:97], v[114:117], v[214:217], v[94:97]
	v_mfma_f32_16x16x32_bf16 v[86:89], v[58:61], v[222:225], v[86:89]
	v_mfma_f32_16x16x32_bf16 v[78:81], v[114:117], v[222:225], v[78:81]
	v_mfma_f32_16x16x32_bf16 v[142:145], v[110:113], v[202:205], v[142:145]
	v_mfma_f32_16x16x32_bf16 v[138:141], v[122:125], v[202:205], v[138:141]
	v_mfma_f32_16x16x32_bf16 v[130:133], v[110:113], v[210:213], v[130:133]
	v_mfma_f32_16x16x32_bf16 v[118:121], v[122:125], v[210:213], v[118:121]
	v_mfma_f32_16x16x32_bf16 v[102:105], v[110:113], v[218:221], v[102:105]
	v_mfma_f32_16x16x32_bf16 v[94:97], v[122:125], v[218:221], v[94:97]
	v_mfma_f32_16x16x32_bf16 v[86:89], v[110:113], v[226:229], v[86:89]
	v_mfma_f32_16x16x32_bf16 v[78:81], v[122:125], v[226:229], v[78:81]
	s_setprio 0
	s_setprio 1
	v_mfma_f32_16x16x32_bf16 v[134:137], v[182:185], v[198:201], v[134:137]
	v_mfma_f32_16x16x32_bf16 v[126:129], v[190:193], v[198:201], v[126:129]
	v_mfma_f32_16x16x32_bf16 v[106:109], v[182:185], v[206:209], v[106:109]
	v_mfma_f32_16x16x32_bf16 v[98:101], v[190:193], v[206:209], v[98:101]
	v_mfma_f32_16x16x32_bf16 v[90:93], v[182:185], v[214:217], v[90:93]
	v_mfma_f32_16x16x32_bf16 v[82:85], v[190:193], v[214:217], v[82:85]
	v_mfma_f32_16x16x32_bf16 v[74:77], v[182:185], v[222:225], v[74:77]
	v_mfma_f32_16x16x32_bf16 v[70:73], v[190:193], v[222:225], v[70:73]
	v_mfma_f32_16x16x32_bf16 v[134:137], v[186:189], v[202:205], v[134:137]
	v_mfma_f32_16x16x32_bf16 v[126:129], v[194:197], v[202:205], v[126:129]
	v_mfma_f32_16x16x32_bf16 v[106:109], v[186:189], v[210:213], v[106:109]
	v_mfma_f32_16x16x32_bf16 v[98:101], v[194:197], v[210:213], v[98:101]
	v_mfma_f32_16x16x32_bf16 v[90:93], v[186:189], v[218:221], v[90:93]
	v_mfma_f32_16x16x32_bf16 v[82:85], v[194:197], v[218:221], v[82:85]
	v_mfma_f32_16x16x32_bf16 v[74:77], v[186:189], v[226:229], v[74:77]
	v_mfma_f32_16x16x32_bf16 v[70:73], v[194:197], v[226:229], v[70:73]
	s_setprio 0
	s_barrier
	s_add_i32 s26, s55, s37
	v_lshl_add_u64 v[174:175], v[174:175], 0, s[12:13]
	s_mov_b32 m0, s26
	ds_read_b128 v[198:201], v180 offset:49152
	ds_read_b128 v[202:205], v180 offset:50176
	ds_read_b128 v[206:209], v180 offset:51200
	ds_read_b128 v[210:213], v180 offset:52224
	ds_read_b128 v[214:217], v180 offset:53248
	ds_read_b128 v[218:221], v180 offset:54272
	ds_read_b128 v[222:225], v180 offset:55296
	ds_read_b128 v[226:229], v180 offset:56320
	global_load_lds_dwordx4 v[174:175], off
	s_add_i32 m0, s26, 0x2000
	s_add_u32 s26, s30, 0x40080
	v_lshl_add_u64 v[174:175], v[230:231], 0, s[12:13]
	s_addc_u32 s27, s31, 0
	s_add_i32 s30, s56, s37
	global_load_lds_dwordx4 v[174:175], off
	s_mov_b32 m0, s30
	s_nop 0
	global_load_lds_dwordx4 v146, s[26:27]
	s_add_i32 m0, s30, 0x2000
	s_nop 0
	global_load_lds_dwordx4 v148, s[26:27]
	v_lshl_add_u64 v[174:175], v[232:233], 0, s[12:13]
	s_mov_b32 m0, s45
	s_nop 0
	global_load_lds_dwordx4 v[174:175], off
	v_lshl_add_u64 v[174:175], v[234:235], 0, s[12:13]
	s_mov_b32 m0, s46
	s_nop 0
	global_load_lds_dwordx4 v[174:175], off
	s_waitcnt vmcnt(8)
	s_waitcnt lgkmcnt(0)
	s_barrier
	s_setprio 1
	s_waitcnt lgkmcnt(0)
	v_mfma_f32_16x16x32_bf16 v[66:69], v[58:61], v[198:201], v[66:69]
	v_mfma_f32_16x16x32_bf16 v[62:65], v[114:117], v[198:201], v[62:65]
	v_mfma_f32_16x16x32_bf16 v[46:49], v[58:61], v[206:209], v[46:49]
	v_mfma_f32_16x16x32_bf16 v[42:45], v[114:117], v[206:209], v[42:45]
	v_mfma_f32_16x16x32_bf16 v[30:33], v[58:61], v[214:217], v[30:33]
	v_mfma_f32_16x16x32_bf16 v[26:29], v[114:117], v[214:217], v[26:29]
	v_mfma_f32_16x16x32_bf16 v[14:17], v[58:61], v[222:225], v[14:17]
	v_mfma_f32_16x16x32_bf16 v[10:13], v[114:117], v[222:225], v[10:13]
	v_mfma_f32_16x16x32_bf16 v[66:69], v[110:113], v[202:205], v[66:69]
	v_mfma_f32_16x16x32_bf16 v[62:65], v[122:125], v[202:205], v[62:65]
	v_mfma_f32_16x16x32_bf16 v[46:49], v[110:113], v[210:213], v[46:49]
	v_mfma_f32_16x16x32_bf16 v[42:45], v[122:125], v[210:213], v[42:45]
	v_mfma_f32_16x16x32_bf16 v[30:33], v[110:113], v[218:221], v[30:33]
	v_mfma_f32_16x16x32_bf16 v[26:29], v[122:125], v[218:221], v[26:29]
	v_mfma_f32_16x16x32_bf16 v[14:17], v[110:113], v[226:229], v[14:17]
	v_mfma_f32_16x16x32_bf16 v[10:13], v[122:125], v[226:229], v[10:13]
	s_setprio 0
	s_setprio 1
	v_mfma_f32_16x16x32_bf16 v[54:57], v[182:185], v[198:201], v[54:57]
	v_mfma_f32_16x16x32_bf16 v[50:53], v[190:193], v[198:201], v[50:53]
	v_mfma_f32_16x16x32_bf16 v[38:41], v[182:185], v[206:209], v[38:41]
	v_mfma_f32_16x16x32_bf16 v[34:37], v[190:193], v[206:209], v[34:37]
	v_mfma_f32_16x16x32_bf16 v[22:25], v[182:185], v[214:217], v[22:25]
	v_mfma_f32_16x16x32_bf16 v[18:21], v[190:193], v[214:217], v[18:21]
	v_mfma_f32_16x16x32_bf16 v[6:9], v[182:185], v[222:225], v[6:9]
	v_mfma_f32_16x16x32_bf16 v[2:5], v[190:193], v[222:225], v[2:5]
	v_mfma_f32_16x16x32_bf16 v[54:57], v[186:189], v[202:205], v[54:57]
	v_mfma_f32_16x16x32_bf16 v[50:53], v[194:197], v[202:205], v[50:53]
	v_mfma_f32_16x16x32_bf16 v[38:41], v[186:189], v[210:213], v[38:41]
	v_mfma_f32_16x16x32_bf16 v[34:37], v[194:197], v[210:213], v[34:37]
	v_mfma_f32_16x16x32_bf16 v[22:25], v[186:189], v[218:221], v[22:25]
	v_mfma_f32_16x16x32_bf16 v[18:21], v[194:197], v[218:221], v[18:21]
	v_mfma_f32_16x16x32_bf16 v[6:9], v[186:189], v[226:229], v[6:9]
	v_mfma_f32_16x16x32_bf16 v[2:5], v[194:197], v[226:229], v[2:5]
	s_setprio 0
	s_barrier
	s_add_i32 s54, s54, 2
	s_add_u32 s52, s52, 0x100
	s_addc_u32 s53, s53, 0
	s_cmp_gt_u32 s54, 13
	s_mov_b64 s[26:27], s[28:29]
	s_cbranch_scc0 .LBB0_1101
	s_and_b64 vcc, exec, s[14:15]
	s_cbranch_vccz .LBB0_1104
	s_barrier

.LBB0_1367:
	ds_read_b128 v[158:161], v178
	ds_read_b128 v[162:165], v178 offset:1024
	ds_read_b128 v[166:169], v178 offset:2048
	ds_read_b128 v[170:173], v178 offset:3072
	ds_read_b128 v[182:185], v179
	ds_read_b128 v[186:189], v179 offset:1024
	ds_read_b128 v[190:193], v179 offset:2048
	ds_read_b128 v[194:197], v179 offset:3072
	s_add_u32 s22, s20, 0x100
	s_addc_u32 s23, s21, 0
	s_cmp_eq_u32 s50, 40
	s_cselect_b32 s27, s7, s23
	s_cselect_b32 s26, s6, s22
	s_cselect_b32 s25, s19, s49
	s_cselect_b32 s24, s18, s2
	v_lshl_add_u64 v[174:175], s[20:21], 0, v[150:151]
	s_add_i32 m0, s31, 0xc000
	ds_read_b128 v[198:201], v180
	ds_read_b128 v[202:205], v180 offset:1024
	ds_read_b128 v[206:209], v180 offset:2048
	ds_read_b128 v[210:213], v180 offset:3072
	ds_read_b128 v[214:217], v180 offset:4096
	ds_read_b128 v[218:221], v180 offset:5120
	ds_read_b128 v[222:225], v180 offset:6144
	ds_read_b128 v[226:229], v180 offset:7168
	global_load_lds_dwordx4 v[174:175], off
	v_lshl_add_u64 v[174:175], s[20:21], 0, v[152:153]
	s_add_i32 m0, s31, 0xe000
	s_nop 0
	global_load_lds_dwordx4 v[174:175], off
	s_waitcnt vmcnt(8)
	s_waitcnt lgkmcnt(0)
	s_barrier
	s_setprio 1
	s_waitcnt lgkmcnt(0)
	v_mfma_f32_16x16x32_bf16 v[126:129], v[158:161], v[198:201], v[126:129]
	v_mfma_f32_16x16x32_bf16 v[122:125], v[166:169], v[198:201], v[122:125]
	v_mfma_f32_16x16x32_bf16 v[114:117], v[158:161], v[206:209], v[114:117]
	v_mfma_f32_16x16x32_bf16 v[106:109], v[166:169], v[206:209], v[106:109]
	v_mfma_f32_16x16x32_bf16 v[98:101], v[158:161], v[214:217], v[98:101]
	v_mfma_f32_16x16x32_bf16 v[90:93], v[166:169], v[214:217], v[90:93]
	v_mfma_f32_16x16x32_bf16 v[78:81], v[158:161], v[222:225], v[78:81]
	v_mfma_f32_16x16x32_bf16 v[74:77], v[166:169], v[222:225], v[74:77]
	v_mfma_f32_16x16x32_bf16 v[126:129], v[162:165], v[202:205], v[126:129]
	v_mfma_f32_16x16x32_bf16 v[122:125], v[170:173], v[202:205], v[122:125]
	v_mfma_f32_16x16x32_bf16 v[114:117], v[162:165], v[210:213], v[114:117]
	v_mfma_f32_16x16x32_bf16 v[106:109], v[170:173], v[210:213], v[106:109]
	v_mfma_f32_16x16x32_bf16 v[98:101], v[162:165], v[218:221], v[98:101]
	v_mfma_f32_16x16x32_bf16 v[90:93], v[170:173], v[218:221], v[90:93]
	v_mfma_f32_16x16x32_bf16 v[78:81], v[162:165], v[226:229], v[78:81]
	v_mfma_f32_16x16x32_bf16 v[74:77], v[170:173], v[226:229], v[74:77]
	s_setprio 0
	s_setprio 1
	v_mfma_f32_16x16x32_bf16 v[118:121], v[182:185], v[198:201], v[118:121]
	v_mfma_f32_16x16x32_bf16 v[110:113], v[190:193], v[198:201], v[110:113]
	v_mfma_f32_16x16x32_bf16 v[102:105], v[182:185], v[206:209], v[102:105]
	v_mfma_f32_16x16x32_bf16 v[94:97], v[190:193], v[206:209], v[94:97]
	v_mfma_f32_16x16x32_bf16 v[86:89], v[182:185], v[214:217], v[86:89]
	v_mfma_f32_16x16x32_bf16 v[82:85], v[190:193], v[214:217], v[82:85]
	v_mfma_f32_16x16x32_bf16 v[70:73], v[182:185], v[222:225], v[70:73]
	v_mfma_f32_16x16x32_bf16 v[66:69], v[190:193], v[222:225], v[66:69]
	v_mfma_f32_16x16x32_bf16 v[118:121], v[186:189], v[202:205], v[118:121]
	v_mfma_f32_16x16x32_bf16 v[110:113], v[194:197], v[202:205], v[110:113]
	v_mfma_f32_16x16x32_bf16 v[102:105], v[186:189], v[210:213], v[102:105]
	v_mfma_f32_16x16x32_bf16 v[94:97], v[194:197], v[210:213], v[94:97]
	v_mfma_f32_16x16x32_bf16 v[86:89], v[186:189], v[218:221], v[86:89]
	v_mfma_f32_16x16x32_bf16 v[82:85], v[194:197], v[218:221], v[82:85]
	v_mfma_f32_16x16x32_bf16 v[70:73], v[186:189], v[226:229], v[70:73]
	v_mfma_f32_16x16x32_bf16 v[66:69], v[194:197], v[226:229], v[66:69]
	s_setprio 0
	s_barrier
	s_add_i32 s20, s43, s30
	v_lshl_add_u64 v[174:175], s[24:25], 0, v[130:131]
	s_mov_b32 m0, s20
	ds_read_b128 v[198:201], v180 offset:16384
	ds_read_b128 v[202:205], v180 offset:17408
	ds_read_b128 v[206:209], v180 offset:18432
	ds_read_b128 v[210:213], v180 offset:19456
	ds_read_b128 v[214:217], v180 offset:20480
	ds_read_b128 v[218:221], v180 offset:21504
	ds_read_b128 v[222:225], v180 offset:22528
	ds_read_b128 v[226:229], v180 offset:23552
	global_load_lds_dwordx4 v130, s[24:25]
	s_add_i32 m0, s20, 0x2000
	s_add_u32 s20, s24, 0xb0000
	v_lshl_add_u64 v[230:231], s[24:25], 0, v[132:133]
	s_addc_u32 s21, s25, 0
	s_add_i32 s51, s44, s30
	global_load_lds_dwordx4 v132, s[24:25]
	s_mov_b32 m0, s51
	v_lshl_add_u64 v[234:235], s[26:27], 0, v[132:133]
	global_load_lds_dwordx4 v130, s[20:21]
	s_add_i32 m0, s51, 0x2000
	s_nop 0
	global_load_lds_dwordx4 v132, s[20:21]
	v_lshl_add_u64 v[232:233], s[26:27], 0, v[130:131]
	s_mov_b32 m0, s31
	s_nop 0
	global_load_lds_dwordx4 v130, s[26:27]
	s_mov_b32 m0, s33
	s_nop 0
	global_load_lds_dwordx4 v132, s[26:27]
	s_waitcnt vmcnt(8)
	s_waitcnt lgkmcnt(0)
	s_barrier
	s_setprio 1
	s_waitcnt lgkmcnt(0)
	v_mfma_f32_16x16x32_bf16 v[62:65], v[158:161], v[198:201], v[62:65]
	v_mfma_f32_16x16x32_bf16 v[58:61], v[166:169], v[198:201], v[58:61]
	v_mfma_f32_16x16x32_bf16 v[46:49], v[158:161], v[206:209], v[46:49]
	v_mfma_f32_16x16x32_bf16 v[42:45], v[166:169], v[206:209], v[42:45]
	v_mfma_f32_16x16x32_bf16 v[30:33], v[158:161], v[214:217], v[30:33]
	v_mfma_f32_16x16x32_bf16 v[26:29], v[166:169], v[214:217], v[26:29]
	v_mfma_f32_16x16x32_bf16 v[14:17], v[158:161], v[222:225], v[14:17]
	v_mfma_f32_16x16x32_bf16 v[10:13], v[166:169], v[222:225], v[10:13]
	v_mfma_f32_16x16x32_bf16 v[62:65], v[162:165], v[202:205], v[62:65]
	v_mfma_f32_16x16x32_bf16 v[58:61], v[170:173], v[202:205], v[58:61]
	v_mfma_f32_16x16x32_bf16 v[46:49], v[162:165], v[210:213], v[46:49]
	v_mfma_f32_16x16x32_bf16 v[42:45], v[170:173], v[210:213], v[42:45]
	v_mfma_f32_16x16x32_bf16 v[30:33], v[162:165], v[218:221], v[30:33]
	v_mfma_f32_16x16x32_bf16 v[26:29], v[170:173], v[218:221], v[26:29]
	v_mfma_f32_16x16x32_bf16 v[14:17], v[162:165], v[226:229], v[14:17]
	v_mfma_f32_16x16x32_bf16 v[10:13], v[170:173], v[226:229], v[10:13]
	s_setprio 0
	s_setprio 1
	v_mfma_f32_16x16x32_bf16 v[54:57], v[182:185], v[198:201], v[54:57]
	v_mfma_f32_16x16x32_bf16 v[50:53], v[190:193], v[198:201], v[50:53]
	v_mfma_f32_16x16x32_bf16 v[38:41], v[182:185], v[206:209], v[38:41]
	v_mfma_f32_16x16x32_bf16 v[34:37], v[190:193], v[206:209], v[34:37]
	v_mfma_f32_16x16x32_bf16 v[22:25], v[182:185], v[214:217], v[22:25]
	v_mfma_f32_16x16x32_bf16 v[18:21], v[190:193], v[214:217], v[18:21]
	v_mfma_f32_16x16x32_bf16 v[6:9], v[182:185], v[222:225], v[6:9]
	v_mfma_f32_16x16x32_bf16 v[2:5], v[190:193], v[222:225], v[2:5]
	v_mfma_f32_16x16x32_bf16 v[54:57], v[186:189], v[202:205], v[54:57]
	v_mfma_f32_16x16x32_bf16 v[50:53], v[194:197], v[202:205], v[50:53]
	v_mfma_f32_16x16x32_bf16 v[38:41], v[186:189], v[210:213], v[38:41]
	v_mfma_f32_16x16x32_bf16 v[34:37], v[194:197], v[210:213], v[34:37]
	v_mfma_f32_16x16x32_bf16 v[22:25], v[186:189], v[218:221], v[22:25]
	v_mfma_f32_16x16x32_bf16 v[18:21], v[194:197], v[218:221], v[18:21]
	v_mfma_f32_16x16x32_bf16 v[6:9], v[186:189], v[226:229], v[6:9]
	v_mfma_f32_16x16x32_bf16 v[2:5], v[194:197], v[226:229], v[2:5]
	s_setprio 0
	s_barrier
	s_add_i32 s51, 0, 0x18000
	s_add_i32 s52, 0, 0x1c000
	v_add_u32_e32 v170, s51, v176
	v_add_u32_e32 v181, s52, v176
	ds_read_b128 v[158:161], v170
	ds_read_b128 v[162:165], v170 offset:1024
	ds_read_b128 v[166:169], v170 offset:2048
	ds_read_b128 v[170:173], v170 offset:3072
	ds_read_b128 v[182:185], v181
	ds_read_b128 v[186:189], v181 offset:1024
	ds_read_b128 v[190:193], v181 offset:2048
	ds_read_b128 v[194:197], v181 offset:3072
	s_add_u32 s20, s26, 0xb0000
	s_addc_u32 s21, s27, 0
	s_mov_b32 m0, s34
	ds_read_b128 v[198:201], v180 offset:32768
	ds_read_b128 v[202:205], v180 offset:33792
	ds_read_b128 v[206:209], v180 offset:34816
	ds_read_b128 v[210:213], v180 offset:35840
	ds_read_b128 v[214:217], v180 offset:36864
	ds_read_b128 v[218:221], v180 offset:37888
	ds_read_b128 v[222:225], v180 offset:38912
	ds_read_b128 v[226:229], v180 offset:39936
	global_load_lds_dwordx4 v130, s[20:21]
	s_mov_b32 m0, s35
	s_nop 0
	global_load_lds_dwordx4 v132, s[20:21]
	s_waitcnt vmcnt(8)
	s_waitcnt lgkmcnt(0)
	s_barrier
	s_setprio 1
	s_waitcnt lgkmcnt(0)
	v_mfma_f32_16x16x32_bf16 v[126:129], v[158:161], v[198:201], v[126:129]
	v_mfma_f32_16x16x32_bf16 v[122:125], v[166:169], v[198:201], v[122:125]
	v_mfma_f32_16x16x32_bf16 v[114:117], v[158:161], v[206:209], v[114:117]
	v_mfma_f32_16x16x32_bf16 v[106:109], v[166:169], v[206:209], v[106:109]
	v_mfma_f32_16x16x32_bf16 v[98:101], v[158:161], v[214:217], v[98:101]
	v_mfma_f32_16x16x32_bf16 v[90:93], v[166:169], v[214:217], v[90:93]
	v_mfma_f32_16x16x32_bf16 v[78:81], v[158:161], v[222:225], v[78:81]
	v_mfma_f32_16x16x32_bf16 v[74:77], v[166:169], v[222:225], v[74:77]
	v_mfma_f32_16x16x32_bf16 v[126:129], v[162:165], v[202:205], v[126:129]
	v_mfma_f32_16x16x32_bf16 v[122:125], v[170:173], v[202:205], v[122:125]
	v_mfma_f32_16x16x32_bf16 v[114:117], v[162:165], v[210:213], v[114:117]
	v_mfma_f32_16x16x32_bf16 v[106:109], v[170:173], v[210:213], v[106:109]
	v_mfma_f32_16x16x32_bf16 v[98:101], v[162:165], v[218:221], v[98:101]
	v_mfma_f32_16x16x32_bf16 v[90:93], v[170:173], v[218:221], v[90:93]
	v_mfma_f32_16x16x32_bf16 v[78:81], v[162:165], v[226:229], v[78:81]
	v_mfma_f32_16x16x32_bf16 v[74:77], v[170:173], v[226:229], v[74:77]
	s_setprio 0
	s_setprio 1
	v_mfma_f32_16x16x32_bf16 v[118:121], v[182:185], v[198:201], v[118:121]
	v_mfma_f32_16x16x32_bf16 v[110:113], v[190:193], v[198:201], v[110:113]
	v_mfma_f32_16x16x32_bf16 v[102:105], v[182:185], v[206:209], v[102:105]
	v_mfma_f32_16x16x32_bf16 v[94:97], v[190:193], v[206:209], v[94:97]
	v_mfma_f32_16x16x32_bf16 v[86:89], v[182:185], v[214:217], v[86:89]
	v_mfma_f32_16x16x32_bf16 v[82:85], v[190:193], v[214:217], v[82:85]
	v_mfma_f32_16x16x32_bf16 v[70:73], v[182:185], v[222:225], v[70:73]
	v_mfma_f32_16x16x32_bf16 v[66:69], v[190:193], v[222:225], v[66:69]
	v_mfma_f32_16x16x32_bf16 v[118:121], v[186:189], v[202:205], v[118:121]
	v_mfma_f32_16x16x32_bf16 v[110:113], v[194:197], v[202:205], v[110:113]
	v_mfma_f32_16x16x32_bf16 v[102:105], v[186:189], v[210:213], v[102:105]
	v_mfma_f32_16x16x32_bf16 v[94:97], v[194:197], v[210:213], v[94:97]
	v_mfma_f32_16x16x32_bf16 v[86:89], v[186:189], v[218:221], v[86:89]
	v_mfma_f32_16x16x32_bf16 v[82:85], v[194:197], v[218:221], v[82:85]
	v_mfma_f32_16x16x32_bf16 v[70:73], v[186:189], v[226:229], v[70:73]
	v_mfma_f32_16x16x32_bf16 v[66:69], v[194:197], v[226:229], v[66:69]
	s_setprio 0
	s_barrier
	s_add_i32 s20, s51, s30
	v_lshl_add_u64 v[174:175], v[174:175], 0, s[14:15]
	s_mov_b32 m0, s20
	ds_read_b128 v[198:201], v180 offset:49152
	ds_read_b128 v[202:205], v180 offset:50176
	ds_read_b128 v[206:209], v180 offset:51200
	ds_read_b128 v[210:213], v180 offset:52224
	ds_read_b128 v[214:217], v180 offset:53248
	ds_read_b128 v[218:221], v180 offset:54272
	ds_read_b128 v[222:225], v180 offset:55296
	ds_read_b128 v[226:229], v180 offset:56320
	global_load_lds_dwordx4 v[174:175], off
	s_add_i32 m0, s20, 0x2000
	s_add_u32 s20, s24, 0xb0080
	v_lshl_add_u64 v[174:175], v[230:231], 0, s[14:15]
	s_addc_u32 s21, s25, 0
	s_add_i32 s24, s52, s30
	global_load_lds_dwordx4 v[174:175], off
	s_mov_b32 m0, s24
	s_nop 0
	global_load_lds_dwordx4 v130, s[20:21]
	s_add_i32 m0, s24, 0x2000
	s_nop 0
	global_load_lds_dwordx4 v132, s[20:21]
	v_lshl_add_u64 v[174:175], v[232:233], 0, s[14:15]
	s_mov_b32 m0, s39
	s_nop 0
	global_load_lds_dwordx4 v[174:175], off
	v_lshl_add_u64 v[174:175], v[234:235], 0, s[14:15]
	s_mov_b32 m0, s40
	s_nop 0
	global_load_lds_dwordx4 v[174:175], off
	s_waitcnt vmcnt(8)
	s_waitcnt lgkmcnt(0)
	s_barrier
	s_setprio 1
	s_waitcnt lgkmcnt(0)
	v_mfma_f32_16x16x32_bf16 v[62:65], v[158:161], v[198:201], v[62:65]
	v_mfma_f32_16x16x32_bf16 v[58:61], v[166:169], v[198:201], v[58:61]
	v_mfma_f32_16x16x32_bf16 v[46:49], v[158:161], v[206:209], v[46:49]
	v_mfma_f32_16x16x32_bf16 v[42:45], v[166:169], v[206:209], v[42:45]
	v_mfma_f32_16x16x32_bf16 v[30:33], v[158:161], v[214:217], v[30:33]
	v_mfma_f32_16x16x32_bf16 v[26:29], v[166:169], v[214:217], v[26:29]
	v_mfma_f32_16x16x32_bf16 v[14:17], v[158:161], v[222:225], v[14:17]
	v_mfma_f32_16x16x32_bf16 v[10:13], v[166:169], v[222:225], v[10:13]
	v_mfma_f32_16x16x32_bf16 v[62:65], v[162:165], v[202:205], v[62:65]
	v_mfma_f32_16x16x32_bf16 v[58:61], v[170:173], v[202:205], v[58:61]
	v_mfma_f32_16x16x32_bf16 v[46:49], v[162:165], v[210:213], v[46:49]
	v_mfma_f32_16x16x32_bf16 v[42:45], v[170:173], v[210:213], v[42:45]
	v_mfma_f32_16x16x32_bf16 v[30:33], v[162:165], v[218:221], v[30:33]
	v_mfma_f32_16x16x32_bf16 v[26:29], v[170:173], v[218:221], v[26:29]
	v_mfma_f32_16x16x32_bf16 v[14:17], v[162:165], v[226:229], v[14:17]
	v_mfma_f32_16x16x32_bf16 v[10:13], v[170:173], v[226:229], v[10:13]
	s_setprio 0
	s_setprio 1
	v_mfma_f32_16x16x32_bf16 v[54:57], v[182:185], v[198:201], v[54:57]
	v_mfma_f32_16x16x32_bf16 v[50:53], v[190:193], v[198:201], v[50:53]
	v_mfma_f32_16x16x32_bf16 v[38:41], v[182:185], v[206:209], v[38:41]
	v_mfma_f32_16x16x32_bf16 v[34:37], v[190:193], v[206:209], v[34:37]
	v_mfma_f32_16x16x32_bf16 v[22:25], v[182:185], v[214:217], v[22:25]
	v_mfma_f32_16x16x32_bf16 v[18:21], v[190:193], v[214:217], v[18:21]
	v_mfma_f32_16x16x32_bf16 v[6:9], v[182:185], v[222:225], v[6:9]
	v_mfma_f32_16x16x32_bf16 v[2:5], v[190:193], v[222:225], v[2:5]
	v_mfma_f32_16x16x32_bf16 v[54:57], v[186:189], v[202:205], v[54:57]
	v_mfma_f32_16x16x32_bf16 v[50:53], v[194:197], v[202:205], v[50:53]
	v_mfma_f32_16x16x32_bf16 v[38:41], v[186:189], v[210:213], v[38:41]
	v_mfma_f32_16x16x32_bf16 v[34:37], v[194:197], v[210:213], v[34:37]
	v_mfma_f32_16x16x32_bf16 v[22:25], v[186:189], v[218:221], v[22:25]
	v_mfma_f32_16x16x32_bf16 v[18:21], v[194:197], v[218:221], v[18:21]
	v_mfma_f32_16x16x32_bf16 v[6:9], v[186:189], v[226:229], v[6:9]
	v_mfma_f32_16x16x32_bf16 v[2:5], v[194:197], v[226:229], v[2:5]
	s_setprio 0
	s_barrier
	s_add_i32 s50, s50, 2
	s_add_u32 s2, s2, 0x100
	s_addc_u32 s49, s49, 0
	s_cmp_gt_u32 s50, 41
	s_mov_b64 s[20:21], s[22:23]
	s_cbranch_scc0 .LBB0_1367
	s_and_b64 vcc, exec, s[16:17]
	s_cbranch_vccz .LBB0_1370
	s_barrier

.LBB0_2328:
	ds_read_b128 v[86:89], v178
	ds_read_b128 v[126:129], v178 offset:1024
	ds_read_b128 v[130:133], v178 offset:2048
	ds_read_b128 v[138:141], v178 offset:3072
	ds_read_b128 v[182:185], v179
	ds_read_b128 v[186:189], v179 offset:1024
	ds_read_b128 v[190:193], v179 offset:2048
	ds_read_b128 v[194:197], v179 offset:3072
	s_add_u32 s24, s22, 0x100
	s_addc_u32 s25, s23, 0
	s_cmp_eq_u32 s55, 12
	s_cselect_b32 s29, s2, s25
	s_cselect_b32 s28, s15, s24
	s_cselect_b32 s27, s13, s54
	s_cselect_b32 s26, s52, s53
	v_lshl_add_u64 v[174:175], s[22:23], 0, v[166:167]
	s_add_i32 m0, s36, 0xc000
	ds_read_b128 v[198:201], v180
	ds_read_b128 v[202:205], v180 offset:1024
	ds_read_b128 v[206:209], v180 offset:2048
	ds_read_b128 v[210:213], v180 offset:3072
	ds_read_b128 v[214:217], v180 offset:4096
	ds_read_b128 v[218:221], v180 offset:5120
	ds_read_b128 v[222:225], v180 offset:6144
	ds_read_b128 v[226:229], v180 offset:7168
	global_load_lds_dwordx4 v[174:175], off
	v_lshl_add_u64 v[174:175], s[22:23], 0, v[168:169]
	s_add_i32 m0, s36, 0xe000
	s_nop 0
	global_load_lds_dwordx4 v[174:175], off
	s_waitcnt vmcnt(8)
	s_waitcnt lgkmcnt(0)
	s_barrier
	s_setprio 1
	s_waitcnt lgkmcnt(0)
	v_mfma_f32_16x16x32_bf16 v[142:145], v[86:89], v[198:201], v[142:145]
	v_mfma_f32_16x16x32_bf16 v[134:137], v[130:133], v[198:201], v[134:137]
	v_mfma_f32_16x16x32_bf16 v[118:121], v[86:89], v[206:209], v[118:121]
	v_mfma_f32_16x16x32_bf16 v[110:113], v[130:133], v[206:209], v[110:113]
	v_mfma_f32_16x16x32_bf16 v[102:105], v[86:89], v[214:217], v[102:105]
	v_mfma_f32_16x16x32_bf16 v[94:97], v[130:133], v[214:217], v[94:97]
	v_mfma_f32_16x16x32_bf16 v[82:85], v[86:89], v[222:225], v[82:85]
	v_mfma_f32_16x16x32_bf16 v[74:77], v[130:133], v[222:225], v[74:77]
	v_mfma_f32_16x16x32_bf16 v[142:145], v[126:129], v[202:205], v[142:145]
	v_mfma_f32_16x16x32_bf16 v[134:137], v[138:141], v[202:205], v[134:137]
	v_mfma_f32_16x16x32_bf16 v[118:121], v[126:129], v[210:213], v[118:121]
	v_mfma_f32_16x16x32_bf16 v[110:113], v[138:141], v[210:213], v[110:113]
	v_mfma_f32_16x16x32_bf16 v[102:105], v[126:129], v[218:221], v[102:105]
	v_mfma_f32_16x16x32_bf16 v[94:97], v[138:141], v[218:221], v[94:97]
	v_mfma_f32_16x16x32_bf16 v[82:85], v[126:129], v[226:229], v[82:85]
	v_mfma_f32_16x16x32_bf16 v[74:77], v[138:141], v[226:229], v[74:77]
	s_setprio 0
	s_setprio 1
	v_mfma_f32_16x16x32_bf16 v[122:125], v[182:185], v[198:201], v[122:125]
	v_mfma_f32_16x16x32_bf16 v[114:117], v[190:193], v[198:201], v[114:117]
	v_mfma_f32_16x16x32_bf16 v[106:109], v[182:185], v[206:209], v[106:109]
	v_mfma_f32_16x16x32_bf16 v[98:101], v[190:193], v[206:209], v[98:101]
	v_mfma_f32_16x16x32_bf16 v[90:93], v[182:185], v[214:217], v[90:93]
	v_mfma_f32_16x16x32_bf16 v[78:81], v[190:193], v[214:217], v[78:81]
	v_mfma_f32_16x16x32_bf16 v[70:73], v[182:185], v[222:225], v[70:73]
	v_mfma_f32_16x16x32_bf16 v[66:69], v[190:193], v[222:225], v[66:69]
	v_mfma_f32_16x16x32_bf16 v[122:125], v[186:189], v[202:205], v[122:125]
	v_mfma_f32_16x16x32_bf16 v[114:117], v[194:197], v[202:205], v[114:117]
	v_mfma_f32_16x16x32_bf16 v[106:109], v[186:189], v[210:213], v[106:109]
	v_mfma_f32_16x16x32_bf16 v[98:101], v[194:197], v[210:213], v[98:101]
	v_mfma_f32_16x16x32_bf16 v[90:93], v[186:189], v[218:221], v[90:93]
	v_mfma_f32_16x16x32_bf16 v[78:81], v[194:197], v[218:221], v[78:81]
	v_mfma_f32_16x16x32_bf16 v[70:73], v[186:189], v[226:229], v[70:73]
	v_mfma_f32_16x16x32_bf16 v[66:69], v[194:197], v[226:229], v[66:69]
	s_setprio 0
	s_barrier
	s_add_i32 s22, s49, s35
	v_lshl_add_u64 v[174:175], s[26:27], 0, v[146:147]
	s_mov_b32 m0, s22
	ds_read_b128 v[198:201], v180 offset:16384
	ds_read_b128 v[202:205], v180 offset:17408
	ds_read_b128 v[206:209], v180 offset:18432
	ds_read_b128 v[210:213], v180 offset:19456
	ds_read_b128 v[214:217], v180 offset:20480
	ds_read_b128 v[218:221], v180 offset:21504
	ds_read_b128 v[222:225], v180 offset:22528
	ds_read_b128 v[226:229], v180 offset:23552
	global_load_lds_dwordx4 v146, s[26:27]
	s_add_i32 m0, s22, 0x2000
	s_add_u32 s22, s26, 0x40000
	v_lshl_add_u64 v[230:231], s[26:27], 0, v[148:149]
	s_addc_u32 s23, s27, 0
	s_add_i32 s56, s50, s35
	global_load_lds_dwordx4 v148, s[26:27]
	s_mov_b32 m0, s56
	v_lshl_add_u64 v[234:235], s[28:29], 0, v[148:149]
	global_load_lds_dwordx4 v146, s[22:23]
	s_add_i32 m0, s56, 0x2000
	s_nop 0
	global_load_lds_dwordx4 v148, s[22:23]
	v_lshl_add_u64 v[232:233], s[28:29], 0, v[146:147]
	s_mov_b32 m0, s36
	s_nop 0
	global_load_lds_dwordx4 v146, s[28:29]
	s_mov_b32 m0, s37
	s_nop 0
	global_load_lds_dwordx4 v148, s[28:29]
	s_waitcnt vmcnt(8)
	s_waitcnt lgkmcnt(0)
	s_barrier
	s_setprio 1
	s_waitcnt lgkmcnt(0)
	v_mfma_f32_16x16x32_bf16 v[62:65], v[86:89], v[198:201], v[62:65]
	v_mfma_f32_16x16x32_bf16 v[58:61], v[130:133], v[198:201], v[58:61]
	v_mfma_f32_16x16x32_bf16 v[46:49], v[86:89], v[206:209], v[46:49]
	v_mfma_f32_16x16x32_bf16 v[42:45], v[130:133], v[206:209], v[42:45]
	v_mfma_f32_16x16x32_bf16 v[30:33], v[86:89], v[214:217], v[30:33]
	v_mfma_f32_16x16x32_bf16 v[26:29], v[130:133], v[214:217], v[26:29]
	v_mfma_f32_16x16x32_bf16 v[18:21], v[86:89], v[222:225], v[18:21]
	v_mfma_f32_16x16x32_bf16 v[10:13], v[130:133], v[222:225], v[10:13]
	v_mfma_f32_16x16x32_bf16 v[62:65], v[126:129], v[202:205], v[62:65]
	v_mfma_f32_16x16x32_bf16 v[58:61], v[138:141], v[202:205], v[58:61]
	v_mfma_f32_16x16x32_bf16 v[46:49], v[126:129], v[210:213], v[46:49]
	v_mfma_f32_16x16x32_bf16 v[42:45], v[138:141], v[210:213], v[42:45]
	v_mfma_f32_16x16x32_bf16 v[30:33], v[126:129], v[218:221], v[30:33]
	v_mfma_f32_16x16x32_bf16 v[26:29], v[138:141], v[218:221], v[26:29]
	v_mfma_f32_16x16x32_bf16 v[18:21], v[126:129], v[226:229], v[18:21]
	v_mfma_f32_16x16x32_bf16 v[10:13], v[138:141], v[226:229], v[10:13]
	s_setprio 0
	s_setprio 1
	v_mfma_f32_16x16x32_bf16 v[54:57], v[182:185], v[198:201], v[54:57]
	v_mfma_f32_16x16x32_bf16 v[50:53], v[190:193], v[198:201], v[50:53]
	v_mfma_f32_16x16x32_bf16 v[38:41], v[182:185], v[206:209], v[38:41]
	v_mfma_f32_16x16x32_bf16 v[34:37], v[190:193], v[206:209], v[34:37]
	v_mfma_f32_16x16x32_bf16 v[22:25], v[182:185], v[214:217], v[22:25]
	v_mfma_f32_16x16x32_bf16 v[14:17], v[190:193], v[214:217], v[14:17]
	v_mfma_f32_16x16x32_bf16 v[6:9], v[182:185], v[222:225], v[6:9]
	v_mfma_f32_16x16x32_bf16 v[2:5], v[190:193], v[222:225], v[2:5]
	v_mfma_f32_16x16x32_bf16 v[54:57], v[186:189], v[202:205], v[54:57]
	v_mfma_f32_16x16x32_bf16 v[50:53], v[194:197], v[202:205], v[50:53]
	v_mfma_f32_16x16x32_bf16 v[38:41], v[186:189], v[210:213], v[38:41]
	v_mfma_f32_16x16x32_bf16 v[34:37], v[194:197], v[210:213], v[34:37]
	v_mfma_f32_16x16x32_bf16 v[22:25], v[186:189], v[218:221], v[22:25]
	v_mfma_f32_16x16x32_bf16 v[14:17], v[194:197], v[218:221], v[14:17]
	v_mfma_f32_16x16x32_bf16 v[6:9], v[186:189], v[226:229], v[6:9]
	v_mfma_f32_16x16x32_bf16 v[2:5], v[194:197], v[226:229], v[2:5]
	s_setprio 0
	s_barrier
	s_add_i32 s56, 0, 0x18000
	s_add_i32 s57, 0, 0x1c000
	v_add_u32_e32 v138, s56, v176
	v_add_u32_e32 v181, s57, v176
	ds_read_b128 v[86:89], v138
	ds_read_b128 v[126:129], v138 offset:1024
	ds_read_b128 v[130:133], v138 offset:2048
	ds_read_b128 v[138:141], v138 offset:3072
	ds_read_b128 v[182:185], v181
	ds_read_b128 v[186:189], v181 offset:1024
	ds_read_b128 v[190:193], v181 offset:2048
	ds_read_b128 v[194:197], v181 offset:3072
	s_add_u32 s22, s28, 0x40000
	s_addc_u32 s23, s29, 0
	s_mov_b32 m0, s38
	ds_read_b128 v[198:201], v180 offset:32768
	ds_read_b128 v[202:205], v180 offset:33792
	ds_read_b128 v[206:209], v180 offset:34816
	ds_read_b128 v[210:213], v180 offset:35840
	ds_read_b128 v[214:217], v180 offset:36864
	ds_read_b128 v[218:221], v180 offset:37888
	ds_read_b128 v[222:225], v180 offset:38912
	ds_read_b128 v[226:229], v180 offset:39936
	global_load_lds_dwordx4 v146, s[22:23]
	s_mov_b32 m0, s39
	s_nop 0
	global_load_lds_dwordx4 v148, s[22:23]
	s_waitcnt vmcnt(8)
	s_waitcnt lgkmcnt(0)
	s_barrier
	s_setprio 1
	s_waitcnt lgkmcnt(0)
	v_mfma_f32_16x16x32_bf16 v[142:145], v[86:89], v[198:201], v[142:145]
	v_mfma_f32_16x16x32_bf16 v[134:137], v[130:133], v[198:201], v[134:137]
	v_mfma_f32_16x16x32_bf16 v[118:121], v[86:89], v[206:209], v[118:121]
	v_mfma_f32_16x16x32_bf16 v[110:113], v[130:133], v[206:209], v[110:113]
	v_mfma_f32_16x16x32_bf16 v[102:105], v[86:89], v[214:217], v[102:105]
	v_mfma_f32_16x16x32_bf16 v[94:97], v[130:133], v[214:217], v[94:97]
	v_mfma_f32_16x16x32_bf16 v[82:85], v[86:89], v[222:225], v[82:85]
	v_mfma_f32_16x16x32_bf16 v[74:77], v[130:133], v[222:225], v[74:77]
	v_mfma_f32_16x16x32_bf16 v[142:145], v[126:129], v[202:205], v[142:145]
	v_mfma_f32_16x16x32_bf16 v[134:137], v[138:141], v[202:205], v[134:137]
	v_mfma_f32_16x16x32_bf16 v[118:121], v[126:129], v[210:213], v[118:121]
	v_mfma_f32_16x16x32_bf16 v[110:113], v[138:141], v[210:213], v[110:113]
	v_mfma_f32_16x16x32_bf16 v[102:105], v[126:129], v[218:221], v[102:105]
	v_mfma_f32_16x16x32_bf16 v[94:97], v[138:141], v[218:221], v[94:97]
	v_mfma_f32_16x16x32_bf16 v[82:85], v[126:129], v[226:229], v[82:85]
	v_mfma_f32_16x16x32_bf16 v[74:77], v[138:141], v[226:229], v[74:77]
	s_setprio 0
	s_setprio 1
	v_mfma_f32_16x16x32_bf16 v[122:125], v[182:185], v[198:201], v[122:125]
	v_mfma_f32_16x16x32_bf16 v[114:117], v[190:193], v[198:201], v[114:117]
	v_mfma_f32_16x16x32_bf16 v[106:109], v[182:185], v[206:209], v[106:109]
	v_mfma_f32_16x16x32_bf16 v[98:101], v[190:193], v[206:209], v[98:101]
	v_mfma_f32_16x16x32_bf16 v[90:93], v[182:185], v[214:217], v[90:93]
	v_mfma_f32_16x16x32_bf16 v[78:81], v[190:193], v[214:217], v[78:81]
	v_mfma_f32_16x16x32_bf16 v[70:73], v[182:185], v[222:225], v[70:73]
	v_mfma_f32_16x16x32_bf16 v[66:69], v[190:193], v[222:225], v[66:69]
	v_mfma_f32_16x16x32_bf16 v[122:125], v[186:189], v[202:205], v[122:125]
	v_mfma_f32_16x16x32_bf16 v[114:117], v[194:197], v[202:205], v[114:117]
	v_mfma_f32_16x16x32_bf16 v[106:109], v[186:189], v[210:213], v[106:109]
	v_mfma_f32_16x16x32_bf16 v[98:101], v[194:197], v[210:213], v[98:101]
	v_mfma_f32_16x16x32_bf16 v[90:93], v[186:189], v[218:221], v[90:93]
	v_mfma_f32_16x16x32_bf16 v[78:81], v[194:197], v[218:221], v[78:81]
	v_mfma_f32_16x16x32_bf16 v[70:73], v[186:189], v[226:229], v[70:73]
	v_mfma_f32_16x16x32_bf16 v[66:69], v[194:197], v[226:229], v[66:69]
	s_setprio 0
	s_barrier
	s_add_i32 s22, s56, s35
	v_lshl_add_u64 v[174:175], v[174:175], 0, s[8:9]
	s_mov_b32 m0, s22
	ds_read_b128 v[198:201], v180 offset:49152
	ds_read_b128 v[202:205], v180 offset:50176
	ds_read_b128 v[206:209], v180 offset:51200
	ds_read_b128 v[210:213], v180 offset:52224
	ds_read_b128 v[214:217], v180 offset:53248
	ds_read_b128 v[218:221], v180 offset:54272
	ds_read_b128 v[222:225], v180 offset:55296
	ds_read_b128 v[226:229], v180 offset:56320
	global_load_lds_dwordx4 v[174:175], off
	s_add_i32 m0, s22, 0x2000
	s_add_u32 s22, s26, 0x40080
	v_lshl_add_u64 v[174:175], v[230:231], 0, s[8:9]
	s_addc_u32 s23, s27, 0
	s_add_i32 s26, s57, s35
	global_load_lds_dwordx4 v[174:175], off
	s_mov_b32 m0, s26
	s_nop 0
	global_load_lds_dwordx4 v146, s[22:23]
	s_add_i32 m0, s26, 0x2000
	s_nop 0
	global_load_lds_dwordx4 v148, s[22:23]
	v_lshl_add_u64 v[174:175], v[232:233], 0, s[8:9]
	s_mov_b32 m0, s45
	s_nop 0
	global_load_lds_dwordx4 v[174:175], off
	v_lshl_add_u64 v[174:175], v[234:235], 0, s[8:9]
	s_mov_b32 m0, s46
	s_nop 0
	global_load_lds_dwordx4 v[174:175], off
	s_waitcnt vmcnt(8)
	s_waitcnt lgkmcnt(0)
	s_barrier
	s_setprio 1
	s_waitcnt lgkmcnt(0)
	v_mfma_f32_16x16x32_bf16 v[62:65], v[86:89], v[198:201], v[62:65]
	v_mfma_f32_16x16x32_bf16 v[58:61], v[130:133], v[198:201], v[58:61]
	v_mfma_f32_16x16x32_bf16 v[46:49], v[86:89], v[206:209], v[46:49]
	v_mfma_f32_16x16x32_bf16 v[42:45], v[130:133], v[206:209], v[42:45]
	v_mfma_f32_16x16x32_bf16 v[30:33], v[86:89], v[214:217], v[30:33]
	v_mfma_f32_16x16x32_bf16 v[26:29], v[130:133], v[214:217], v[26:29]
	v_mfma_f32_16x16x32_bf16 v[18:21], v[86:89], v[222:225], v[18:21]
	v_mfma_f32_16x16x32_bf16 v[10:13], v[130:133], v[222:225], v[10:13]
	v_mfma_f32_16x16x32_bf16 v[62:65], v[126:129], v[202:205], v[62:65]
	v_mfma_f32_16x16x32_bf16 v[58:61], v[138:141], v[202:205], v[58:61]
	v_mfma_f32_16x16x32_bf16 v[46:49], v[126:129], v[210:213], v[46:49]
	v_mfma_f32_16x16x32_bf16 v[42:45], v[138:141], v[210:213], v[42:45]
	v_mfma_f32_16x16x32_bf16 v[30:33], v[126:129], v[218:221], v[30:33]
	v_mfma_f32_16x16x32_bf16 v[26:29], v[138:141], v[218:221], v[26:29]
	v_mfma_f32_16x16x32_bf16 v[18:21], v[126:129], v[226:229], v[18:21]
	v_mfma_f32_16x16x32_bf16 v[10:13], v[138:141], v[226:229], v[10:13]
	s_setprio 0
	s_setprio 1
	v_mfma_f32_16x16x32_bf16 v[54:57], v[182:185], v[198:201], v[54:57]
	v_mfma_f32_16x16x32_bf16 v[50:53], v[190:193], v[198:201], v[50:53]
	v_mfma_f32_16x16x32_bf16 v[38:41], v[182:185], v[206:209], v[38:41]
	v_mfma_f32_16x16x32_bf16 v[34:37], v[190:193], v[206:209], v[34:37]
	v_mfma_f32_16x16x32_bf16 v[22:25], v[182:185], v[214:217], v[22:25]
	v_mfma_f32_16x16x32_bf16 v[14:17], v[190:193], v[214:217], v[14:17]
	v_mfma_f32_16x16x32_bf16 v[6:9], v[182:185], v[222:225], v[6:9]
	v_mfma_f32_16x16x32_bf16 v[2:5], v[190:193], v[222:225], v[2:5]
	v_mfma_f32_16x16x32_bf16 v[54:57], v[186:189], v[202:205], v[54:57]
	v_mfma_f32_16x16x32_bf16 v[50:53], v[194:197], v[202:205], v[50:53]
	v_mfma_f32_16x16x32_bf16 v[38:41], v[186:189], v[210:213], v[38:41]
	v_mfma_f32_16x16x32_bf16 v[34:37], v[194:197], v[210:213], v[34:37]
	v_mfma_f32_16x16x32_bf16 v[22:25], v[186:189], v[218:221], v[22:25]
	v_mfma_f32_16x16x32_bf16 v[14:17], v[194:197], v[218:221], v[14:17]
	v_mfma_f32_16x16x32_bf16 v[6:9], v[186:189], v[226:229], v[6:9]
	v_mfma_f32_16x16x32_bf16 v[2:5], v[194:197], v[226:229], v[2:5]
	s_setprio 0
	s_barrier
	s_add_i32 s55, s55, 2
	s_add_u32 s53, s53, 0x100
	s_addc_u32 s54, s54, 0
	s_cmp_gt_u32 s55, 13
	s_mov_b64 s[22:23], s[24:25]
	s_cbranch_scc0 .LBB0_2328
	s_and_b64 vcc, exec, s[10:11]
	s_cbranch_vccz .LBB0_2331
	s_barrier

.LBB0_2486:
	ds_read_b128 v[154:157], v151
	ds_read_b128 v[158:161], v151 offset:1024
	ds_read_b128 v[162:165], v151 offset:2048
	ds_read_b128 v[166:169], v151 offset:3072
	ds_read_b128 v[170:173], v152
	ds_read_b128 v[174:177], v152 offset:1024
	ds_read_b128 v[178:181], v152 offset:2048
	ds_read_b128 v[182:185], v152 offset:3072
	s_add_u32 s26, s24, 0xfffc0080
	s_addc_u32 s27, s25, -1
	s_cmp_eq_u32 s52, 12
	s_cselect_b32 s29, s17, s27
	s_cselect_b32 s28, s48, s26
	s_cselect_b32 s27, s15, s51
	s_cselect_b32 s26, s49, s50
	s_add_i32 m0, s23, 0xc000
	ds_read_b128 v[186:189], v153
	ds_read_b128 v[190:193], v153 offset:1024
	ds_read_b128 v[194:197], v153 offset:2048
	ds_read_b128 v[198:201], v153 offset:3072
	ds_read_b128 v[202:205], v153 offset:4096
	ds_read_b128 v[206:209], v153 offset:5120
	ds_read_b128 v[210:213], v153 offset:6144
	ds_read_b128 v[214:217], v153 offset:7168
	global_load_lds_dwordx4 v138, s[24:25]
	s_add_i32 m0, s23, 0xe000
	s_nop 0
	global_load_lds_dwordx4 v140, s[24:25]
	s_waitcnt vmcnt(8)
	s_waitcnt lgkmcnt(0)
	s_barrier
	s_setprio 1
	s_waitcnt lgkmcnt(0)
	v_mfma_f32_16x16x32_bf16 v[126:129], v[154:157], v[186:189], v[126:129]
	v_mfma_f32_16x16x32_bf16 v[122:125], v[162:165], v[186:189], v[122:125]
	v_mfma_f32_16x16x32_bf16 v[110:113], v[154:157], v[194:197], v[110:113]
	v_mfma_f32_16x16x32_bf16 v[106:109], v[162:165], v[194:197], v[106:109]
	v_mfma_f32_16x16x32_bf16 v[94:97], v[154:157], v[202:205], v[94:97]
	v_mfma_f32_16x16x32_bf16 v[90:93], v[162:165], v[202:205], v[90:93]
	v_mfma_f32_16x16x32_bf16 v[78:81], v[154:157], v[210:213], v[78:81]
	v_mfma_f32_16x16x32_bf16 v[74:77], v[162:165], v[210:213], v[74:77]
	v_mfma_f32_16x16x32_bf16 v[126:129], v[158:161], v[190:193], v[126:129]
	v_mfma_f32_16x16x32_bf16 v[122:125], v[166:169], v[190:193], v[122:125]
	v_mfma_f32_16x16x32_bf16 v[110:113], v[158:161], v[198:201], v[110:113]
	v_mfma_f32_16x16x32_bf16 v[106:109], v[166:169], v[198:201], v[106:109]
	v_mfma_f32_16x16x32_bf16 v[94:97], v[158:161], v[206:209], v[94:97]
	v_mfma_f32_16x16x32_bf16 v[90:93], v[166:169], v[206:209], v[90:93]
	v_mfma_f32_16x16x32_bf16 v[78:81], v[158:161], v[214:217], v[78:81]
	v_mfma_f32_16x16x32_bf16 v[74:77], v[166:169], v[214:217], v[74:77]
	s_setprio 0
	s_setprio 1
	v_mfma_f32_16x16x32_bf16 v[118:121], v[170:173], v[186:189], v[118:121]
	v_mfma_f32_16x16x32_bf16 v[114:117], v[178:181], v[186:189], v[114:117]
	v_mfma_f32_16x16x32_bf16 v[102:105], v[170:173], v[194:197], v[102:105]
	v_mfma_f32_16x16x32_bf16 v[98:101], v[178:181], v[194:197], v[98:101]
	v_mfma_f32_16x16x32_bf16 v[86:89], v[170:173], v[202:205], v[86:89]
	v_mfma_f32_16x16x32_bf16 v[82:85], v[178:181], v[202:205], v[82:85]
	v_mfma_f32_16x16x32_bf16 v[70:73], v[170:173], v[210:213], v[70:73]
	v_mfma_f32_16x16x32_bf16 v[66:69], v[178:181], v[210:213], v[66:69]
	v_mfma_f32_16x16x32_bf16 v[118:121], v[174:177], v[190:193], v[118:121]
	v_mfma_f32_16x16x32_bf16 v[114:117], v[182:185], v[190:193], v[114:117]
	v_mfma_f32_16x16x32_bf16 v[102:105], v[174:177], v[198:201], v[102:105]
	v_mfma_f32_16x16x32_bf16 v[98:101], v[182:185], v[198:201], v[98:101]
	v_mfma_f32_16x16x32_bf16 v[86:89], v[174:177], v[206:209], v[86:89]
	v_mfma_f32_16x16x32_bf16 v[82:85], v[182:185], v[206:209], v[82:85]
	v_mfma_f32_16x16x32_bf16 v[70:73], v[174:177], v[214:217], v[70:73]
	v_mfma_f32_16x16x32_bf16 v[66:69], v[182:185], v[214:217], v[66:69]
	s_setprio 0
	s_barrier
	s_add_i32 s53, s45, s34
	v_lshl_add_u64 v[146:147], s[26:27], 0, v[134:135]
	s_mov_b32 m0, s53
	ds_read_b128 v[186:189], v153 offset:16384
	ds_read_b128 v[190:193], v153 offset:17408
	ds_read_b128 v[194:197], v153 offset:18432
	ds_read_b128 v[198:201], v153 offset:19456
	ds_read_b128 v[202:205], v153 offset:20480
	ds_read_b128 v[206:209], v153 offset:21504
	ds_read_b128 v[210:213], v153 offset:22528
	ds_read_b128 v[214:217], v153 offset:23552
	global_load_lds_dwordx4 v134, s[26:27]
	s_add_i32 m0, s53, 0x2000
	s_add_u32 s54, s26, 0x40000
	v_lshl_add_u64 v[218:219], s[26:27], 0, v[130:131]
	s_addc_u32 s55, s27, 0
	s_add_i32 s53, s46, s34
	global_load_lds_dwordx4 v130, s[26:27]
	s_mov_b32 m0, s53
	v_lshl_add_u64 v[222:223], s[28:29], 0, v[132:133]
	global_load_lds_dwordx4 v134, s[54:55]
	s_add_i32 m0, s53, 0x2000
	s_nop 0
	global_load_lds_dwordx4 v130, s[54:55]
	v_lshl_add_u64 v[220:221], s[28:29], 0, v[136:137]
	s_mov_b32 m0, s23
	s_nop 0
	global_load_lds_dwordx4 v136, s[28:29]
	s_mov_b32 m0, s37
	s_nop 0
	global_load_lds_dwordx4 v132, s[28:29]
	s_waitcnt vmcnt(8)
	s_waitcnt lgkmcnt(0)
	s_barrier
	s_setprio 1
	s_waitcnt lgkmcnt(0)
	v_mfma_f32_16x16x32_bf16 v[62:65], v[154:157], v[186:189], v[62:65]
	v_mfma_f32_16x16x32_bf16 v[58:61], v[162:165], v[186:189], v[58:61]
	v_mfma_f32_16x16x32_bf16 v[46:49], v[154:157], v[194:197], v[46:49]
	v_mfma_f32_16x16x32_bf16 v[42:45], v[162:165], v[194:197], v[42:45]
	v_mfma_f32_16x16x32_bf16 v[30:33], v[154:157], v[202:205], v[30:33]
	v_mfma_f32_16x16x32_bf16 v[26:29], v[162:165], v[202:205], v[26:29]
	v_mfma_f32_16x16x32_bf16 v[14:17], v[154:157], v[210:213], v[14:17]
	v_mfma_f32_16x16x32_bf16 v[10:13], v[162:165], v[210:213], v[10:13]
	v_mfma_f32_16x16x32_bf16 v[62:65], v[158:161], v[190:193], v[62:65]
	v_mfma_f32_16x16x32_bf16 v[58:61], v[166:169], v[190:193], v[58:61]
	v_mfma_f32_16x16x32_bf16 v[46:49], v[158:161], v[198:201], v[46:49]
	v_mfma_f32_16x16x32_bf16 v[42:45], v[166:169], v[198:201], v[42:45]
	v_mfma_f32_16x16x32_bf16 v[30:33], v[158:161], v[206:209], v[30:33]
	v_mfma_f32_16x16x32_bf16 v[26:29], v[166:169], v[206:209], v[26:29]
	v_mfma_f32_16x16x32_bf16 v[14:17], v[158:161], v[214:217], v[14:17]
	v_mfma_f32_16x16x32_bf16 v[10:13], v[166:169], v[214:217], v[10:13]
	s_setprio 0
	s_setprio 1
	v_mfma_f32_16x16x32_bf16 v[54:57], v[170:173], v[186:189], v[54:57]
	v_mfma_f32_16x16x32_bf16 v[50:53], v[178:181], v[186:189], v[50:53]
	v_mfma_f32_16x16x32_bf16 v[38:41], v[170:173], v[194:197], v[38:41]
	v_mfma_f32_16x16x32_bf16 v[34:37], v[178:181], v[194:197], v[34:37]
	v_mfma_f32_16x16x32_bf16 v[22:25], v[170:173], v[202:205], v[22:25]
	v_mfma_f32_16x16x32_bf16 v[18:21], v[178:181], v[202:205], v[18:21]
	v_mfma_f32_16x16x32_bf16 v[6:9], v[170:173], v[210:213], v[6:9]
	v_mfma_f32_16x16x32_bf16 v[2:5], v[178:181], v[210:213], v[2:5]
	v_mfma_f32_16x16x32_bf16 v[54:57], v[174:177], v[190:193], v[54:57]
	v_mfma_f32_16x16x32_bf16 v[50:53], v[182:185], v[190:193], v[50:53]
	v_mfma_f32_16x16x32_bf16 v[38:41], v[174:177], v[198:201], v[38:41]
	v_mfma_f32_16x16x32_bf16 v[34:37], v[182:185], v[198:201], v[34:37]
	v_mfma_f32_16x16x32_bf16 v[22:25], v[174:177], v[206:209], v[22:25]
	v_mfma_f32_16x16x32_bf16 v[18:21], v[182:185], v[206:209], v[18:21]
	v_mfma_f32_16x16x32_bf16 v[6:9], v[174:177], v[214:217], v[6:9]
	v_mfma_f32_16x16x32_bf16 v[2:5], v[182:185], v[214:217], v[2:5]
	s_setprio 0
	s_barrier
	s_add_i32 s53, 0, 0x18000
	s_add_i32 s54, 0, 0x1c000
	v_add_u32_e32 v166, s53, v149
	v_add_u32_e32 v182, s54, v149
	ds_read_b128 v[154:157], v166
	ds_read_b128 v[158:161], v166 offset:1024
	ds_read_b128 v[162:165], v166 offset:2048
	ds_read_b128 v[166:169], v166 offset:3072
	ds_read_b128 v[170:173], v182
	ds_read_b128 v[174:177], v182 offset:1024
	ds_read_b128 v[178:181], v182 offset:2048
	ds_read_b128 v[182:185], v182 offset:3072
	s_add_u32 s28, s28, 0x40000
	s_addc_u32 s29, s29, 0
	s_mov_b32 m0, s38
	ds_read_b128 v[186:189], v153 offset:32768
	ds_read_b128 v[190:193], v153 offset:33792
	ds_read_b128 v[194:197], v153 offset:34816
	ds_read_b128 v[198:201], v153 offset:35840
	ds_read_b128 v[202:205], v153 offset:36864
	ds_read_b128 v[206:209], v153 offset:37888
	ds_read_b128 v[210:213], v153 offset:38912
	ds_read_b128 v[214:217], v153 offset:39936
	global_load_lds_dwordx4 v136, s[28:29]
	s_mov_b32 m0, s39
	s_nop 0
	global_load_lds_dwordx4 v132, s[28:29]
	s_waitcnt vmcnt(8)
	s_waitcnt lgkmcnt(0)
	s_barrier
	s_setprio 1
	s_waitcnt lgkmcnt(0)
	v_mfma_f32_16x16x32_bf16 v[126:129], v[154:157], v[186:189], v[126:129]
	v_mfma_f32_16x16x32_bf16 v[122:125], v[162:165], v[186:189], v[122:125]
	v_mfma_f32_16x16x32_bf16 v[110:113], v[154:157], v[194:197], v[110:113]
	v_mfma_f32_16x16x32_bf16 v[106:109], v[162:165], v[194:197], v[106:109]
	v_mfma_f32_16x16x32_bf16 v[94:97], v[154:157], v[202:205], v[94:97]
	v_mfma_f32_16x16x32_bf16 v[90:93], v[162:165], v[202:205], v[90:93]
	v_mfma_f32_16x16x32_bf16 v[78:81], v[154:157], v[210:213], v[78:81]
	v_mfma_f32_16x16x32_bf16 v[74:77], v[162:165], v[210:213], v[74:77]
	v_mfma_f32_16x16x32_bf16 v[126:129], v[158:161], v[190:193], v[126:129]
	v_mfma_f32_16x16x32_bf16 v[122:125], v[166:169], v[190:193], v[122:125]
	v_mfma_f32_16x16x32_bf16 v[110:113], v[158:161], v[198:201], v[110:113]
	v_mfma_f32_16x16x32_bf16 v[106:109], v[166:169], v[198:201], v[106:109]
	v_mfma_f32_16x16x32_bf16 v[94:97], v[158:161], v[206:209], v[94:97]
	v_mfma_f32_16x16x32_bf16 v[90:93], v[166:169], v[206:209], v[90:93]
	v_mfma_f32_16x16x32_bf16 v[78:81], v[158:161], v[214:217], v[78:81]
	v_mfma_f32_16x16x32_bf16 v[74:77], v[166:169], v[214:217], v[74:77]
	s_setprio 0
	s_setprio 1
	v_mfma_f32_16x16x32_bf16 v[118:121], v[170:173], v[186:189], v[118:121]
	v_mfma_f32_16x16x32_bf16 v[114:117], v[178:181], v[186:189], v[114:117]
	v_mfma_f32_16x16x32_bf16 v[102:105], v[170:173], v[194:197], v[102:105]
	v_mfma_f32_16x16x32_bf16 v[98:101], v[178:181], v[194:197], v[98:101]
	v_mfma_f32_16x16x32_bf16 v[86:89], v[170:173], v[202:205], v[86:89]
	v_mfma_f32_16x16x32_bf16 v[82:85], v[178:181], v[202:205], v[82:85]
	v_mfma_f32_16x16x32_bf16 v[70:73], v[170:173], v[210:213], v[70:73]
	v_mfma_f32_16x16x32_bf16 v[66:69], v[178:181], v[210:213], v[66:69]
	v_mfma_f32_16x16x32_bf16 v[118:121], v[174:177], v[190:193], v[118:121]
	v_mfma_f32_16x16x32_bf16 v[114:117], v[182:185], v[190:193], v[114:117]
	v_mfma_f32_16x16x32_bf16 v[102:105], v[174:177], v[198:201], v[102:105]
	v_mfma_f32_16x16x32_bf16 v[98:101], v[182:185], v[198:201], v[98:101]
	v_mfma_f32_16x16x32_bf16 v[86:89], v[174:177], v[206:209], v[86:89]
	v_mfma_f32_16x16x32_bf16 v[82:85], v[182:185], v[206:209], v[82:85]
	v_mfma_f32_16x16x32_bf16 v[70:73], v[174:177], v[214:217], v[70:73]
	v_mfma_f32_16x16x32_bf16 v[66:69], v[182:185], v[214:217], v[66:69]
	s_setprio 0
	s_barrier
	s_add_i32 s28, s53, s34
	v_lshl_add_u64 v[146:147], v[146:147], 0, s[10:11]
	s_mov_b32 m0, s28
	ds_read_b128 v[186:189], v153 offset:49152
	ds_read_b128 v[190:193], v153 offset:50176
	ds_read_b128 v[194:197], v153 offset:51200
	ds_read_b128 v[198:201], v153 offset:52224
	ds_read_b128 v[202:205], v153 offset:53248
	ds_read_b128 v[206:209], v153 offset:54272
	ds_read_b128 v[210:213], v153 offset:55296
	ds_read_b128 v[214:217], v153 offset:56320
	global_load_lds_dwordx4 v[146:147], off
	s_add_i32 m0, s28, 0x2000
	s_add_u32 s26, s26, 0x40080
	v_lshl_add_u64 v[146:147], v[218:219], 0, s[10:11]
	s_addc_u32 s27, s27, 0
	s_add_i32 s28, s54, s34
	global_load_lds_dwordx4 v[146:147], off
	s_mov_b32 m0, s28
	s_nop 0
	global_load_lds_dwordx4 v134, s[26:27]
	s_add_i32 m0, s28, 0x2000
	s_nop 0
	global_load_lds_dwordx4 v130, s[26:27]
	v_lshl_add_u64 v[146:147], v[220:221], 0, s[10:11]
	s_mov_b32 m0, s42
	s_nop 0
	global_load_lds_dwordx4 v[146:147], off
	v_lshl_add_u64 v[146:147], v[222:223], 0, s[10:11]
	s_mov_b32 m0, s43
	s_nop 0
	global_load_lds_dwordx4 v[146:147], off
	s_waitcnt vmcnt(8)
	s_waitcnt lgkmcnt(0)
	s_barrier
	s_setprio 1
	s_waitcnt lgkmcnt(0)
	v_mfma_f32_16x16x32_bf16 v[62:65], v[154:157], v[186:189], v[62:65]
	v_mfma_f32_16x16x32_bf16 v[58:61], v[162:165], v[186:189], v[58:61]
	v_mfma_f32_16x16x32_bf16 v[46:49], v[154:157], v[194:197], v[46:49]
	v_mfma_f32_16x16x32_bf16 v[42:45], v[162:165], v[194:197], v[42:45]
	v_mfma_f32_16x16x32_bf16 v[30:33], v[154:157], v[202:205], v[30:33]
	v_mfma_f32_16x16x32_bf16 v[26:29], v[162:165], v[202:205], v[26:29]
	v_mfma_f32_16x16x32_bf16 v[14:17], v[154:157], v[210:213], v[14:17]
	v_mfma_f32_16x16x32_bf16 v[10:13], v[162:165], v[210:213], v[10:13]
	v_mfma_f32_16x16x32_bf16 v[62:65], v[158:161], v[190:193], v[62:65]
	v_mfma_f32_16x16x32_bf16 v[58:61], v[166:169], v[190:193], v[58:61]
	v_mfma_f32_16x16x32_bf16 v[46:49], v[158:161], v[198:201], v[46:49]
	v_mfma_f32_16x16x32_bf16 v[42:45], v[166:169], v[198:201], v[42:45]
	v_mfma_f32_16x16x32_bf16 v[30:33], v[158:161], v[206:209], v[30:33]
	v_mfma_f32_16x16x32_bf16 v[26:29], v[166:169], v[206:209], v[26:29]
	v_mfma_f32_16x16x32_bf16 v[14:17], v[158:161], v[214:217], v[14:17]
	v_mfma_f32_16x16x32_bf16 v[10:13], v[166:169], v[214:217], v[10:13]
	s_setprio 0
	s_setprio 1
	v_mfma_f32_16x16x32_bf16 v[54:57], v[170:173], v[186:189], v[54:57]
	v_mfma_f32_16x16x32_bf16 v[50:53], v[178:181], v[186:189], v[50:53]
	v_mfma_f32_16x16x32_bf16 v[38:41], v[170:173], v[194:197], v[38:41]
	v_mfma_f32_16x16x32_bf16 v[34:37], v[178:181], v[194:197], v[34:37]
	v_mfma_f32_16x16x32_bf16 v[22:25], v[170:173], v[202:205], v[22:25]
	v_mfma_f32_16x16x32_bf16 v[18:21], v[178:181], v[202:205], v[18:21]
	v_mfma_f32_16x16x32_bf16 v[6:9], v[170:173], v[210:213], v[6:9]
	v_mfma_f32_16x16x32_bf16 v[2:5], v[178:181], v[210:213], v[2:5]
	v_mfma_f32_16x16x32_bf16 v[54:57], v[174:177], v[190:193], v[54:57]
	v_mfma_f32_16x16x32_bf16 v[50:53], v[182:185], v[190:193], v[50:53]
	v_mfma_f32_16x16x32_bf16 v[38:41], v[174:177], v[198:201], v[38:41]
	v_mfma_f32_16x16x32_bf16 v[34:37], v[182:185], v[198:201], v[34:37]
	v_mfma_f32_16x16x32_bf16 v[22:25], v[174:177], v[206:209], v[22:25]
	v_mfma_f32_16x16x32_bf16 v[18:21], v[182:185], v[206:209], v[18:21]
	v_mfma_f32_16x16x32_bf16 v[6:9], v[174:177], v[214:217], v[6:9]
	v_mfma_f32_16x16x32_bf16 v[2:5], v[182:185], v[214:217], v[2:5]
	s_setprio 0
	s_barrier
	s_add_i32 s52, s52, 2
	s_add_u32 s24, s24, 0x100
	s_addc_u32 s25, s25, 0
	s_add_u32 s50, s50, 0x100
	s_addc_u32 s51, s51, 0
	s_cmp_gt_u32 s52, 13
	s_cbranch_scc0 .LBB0_2486
	s_and_b64 vcc, exec, s[12:13]
	s_cbranch_vccz .LBB0_2489
	s_barrier

.LBB0_2583:
	ds_read_b128 v[158:161], v178
	ds_read_b128 v[162:165], v178 offset:1024
	ds_read_b128 v[166:169], v178 offset:2048
	ds_read_b128 v[170:173], v178 offset:3072
	ds_read_b128 v[182:185], v179
	ds_read_b128 v[186:189], v179 offset:1024
	ds_read_b128 v[190:193], v179 offset:2048
	ds_read_b128 v[194:197], v179 offset:3072
	s_add_u32 s18, s16, 0x100
	s_addc_u32 s19, s17, 0
	s_cmp_eq_u32 s51, 40
	s_cselect_b32 s23, s7, s19
	s_cselect_b32 s22, s6, s18
	s_cselect_b32 s21, s15, s50
	s_cselect_b32 s20, s14, s2
	v_lshl_add_u64 v[174:175], s[16:17], 0, v[150:151]
	s_add_i32 m0, s29, 0xc000
	ds_read_b128 v[198:201], v180
	ds_read_b128 v[202:205], v180 offset:1024
	ds_read_b128 v[206:209], v180 offset:2048
	ds_read_b128 v[210:213], v180 offset:3072
	ds_read_b128 v[214:217], v180 offset:4096
	ds_read_b128 v[218:221], v180 offset:5120
	ds_read_b128 v[222:225], v180 offset:6144
	ds_read_b128 v[226:229], v180 offset:7168
	global_load_lds_dwordx4 v[174:175], off
	v_lshl_add_u64 v[174:175], s[16:17], 0, v[152:153]
	s_add_i32 m0, s29, 0xe000
	s_nop 0
	global_load_lds_dwordx4 v[174:175], off
	s_waitcnt vmcnt(8)
	s_waitcnt lgkmcnt(0)
	s_barrier
	s_setprio 1
	s_waitcnt lgkmcnt(0)
	v_mfma_f32_16x16x32_bf16 v[126:129], v[158:161], v[198:201], v[126:129]
	v_mfma_f32_16x16x32_bf16 v[122:125], v[166:169], v[198:201], v[122:125]
	v_mfma_f32_16x16x32_bf16 v[114:117], v[158:161], v[206:209], v[114:117]
	v_mfma_f32_16x16x32_bf16 v[106:109], v[166:169], v[206:209], v[106:109]
	v_mfma_f32_16x16x32_bf16 v[98:101], v[158:161], v[214:217], v[98:101]
	v_mfma_f32_16x16x32_bf16 v[90:93], v[166:169], v[214:217], v[90:93]
	v_mfma_f32_16x16x32_bf16 v[78:81], v[158:161], v[222:225], v[78:81]
	v_mfma_f32_16x16x32_bf16 v[74:77], v[166:169], v[222:225], v[74:77]
	v_mfma_f32_16x16x32_bf16 v[126:129], v[162:165], v[202:205], v[126:129]
	v_mfma_f32_16x16x32_bf16 v[122:125], v[170:173], v[202:205], v[122:125]
	v_mfma_f32_16x16x32_bf16 v[114:117], v[162:165], v[210:213], v[114:117]
	v_mfma_f32_16x16x32_bf16 v[106:109], v[170:173], v[210:213], v[106:109]
	v_mfma_f32_16x16x32_bf16 v[98:101], v[162:165], v[218:221], v[98:101]
	v_mfma_f32_16x16x32_bf16 v[90:93], v[170:173], v[218:221], v[90:93]
	v_mfma_f32_16x16x32_bf16 v[78:81], v[162:165], v[226:229], v[78:81]
	v_mfma_f32_16x16x32_bf16 v[74:77], v[170:173], v[226:229], v[74:77]
	s_setprio 0
	s_setprio 1
	v_mfma_f32_16x16x32_bf16 v[118:121], v[182:185], v[198:201], v[118:121]
	v_mfma_f32_16x16x32_bf16 v[110:113], v[190:193], v[198:201], v[110:113]
	v_mfma_f32_16x16x32_bf16 v[102:105], v[182:185], v[206:209], v[102:105]
	v_mfma_f32_16x16x32_bf16 v[94:97], v[190:193], v[206:209], v[94:97]
	v_mfma_f32_16x16x32_bf16 v[86:89], v[182:185], v[214:217], v[86:89]
	v_mfma_f32_16x16x32_bf16 v[82:85], v[190:193], v[214:217], v[82:85]
	v_mfma_f32_16x16x32_bf16 v[70:73], v[182:185], v[222:225], v[70:73]
	v_mfma_f32_16x16x32_bf16 v[66:69], v[190:193], v[222:225], v[66:69]
	v_mfma_f32_16x16x32_bf16 v[118:121], v[186:189], v[202:205], v[118:121]
	v_mfma_f32_16x16x32_bf16 v[110:113], v[194:197], v[202:205], v[110:113]
	v_mfma_f32_16x16x32_bf16 v[102:105], v[186:189], v[210:213], v[102:105]
	v_mfma_f32_16x16x32_bf16 v[94:97], v[194:197], v[210:213], v[94:97]
	v_mfma_f32_16x16x32_bf16 v[86:89], v[186:189], v[218:221], v[86:89]
	v_mfma_f32_16x16x32_bf16 v[82:85], v[194:197], v[218:221], v[82:85]
	v_mfma_f32_16x16x32_bf16 v[70:73], v[186:189], v[226:229], v[70:73]
	v_mfma_f32_16x16x32_bf16 v[66:69], v[194:197], v[226:229], v[66:69]
	s_setprio 0
	s_barrier
	s_add_i32 s16, s43, s28
	v_lshl_add_u64 v[174:175], s[20:21], 0, v[130:131]
	s_mov_b32 m0, s16
	ds_read_b128 v[198:201], v180 offset:16384
	ds_read_b128 v[202:205], v180 offset:17408
	ds_read_b128 v[206:209], v180 offset:18432
	ds_read_b128 v[210:213], v180 offset:19456
	ds_read_b128 v[214:217], v180 offset:20480
	ds_read_b128 v[218:221], v180 offset:21504
	ds_read_b128 v[222:225], v180 offset:22528
	ds_read_b128 v[226:229], v180 offset:23552
	global_load_lds_dwordx4 v130, s[20:21]
	s_add_i32 m0, s16, 0x2000
	s_add_u32 s16, s20, 0xb0000
	v_lshl_add_u64 v[230:231], s[20:21], 0, v[132:133]
	s_addc_u32 s17, s21, 0
	s_add_i32 s52, s44, s28
	global_load_lds_dwordx4 v132, s[20:21]
	s_mov_b32 m0, s52
	v_lshl_add_u64 v[234:235], s[22:23], 0, v[132:133]
	global_load_lds_dwordx4 v130, s[16:17]
	s_add_i32 m0, s52, 0x2000
	s_nop 0
	global_load_lds_dwordx4 v132, s[16:17]
	v_lshl_add_u64 v[232:233], s[22:23], 0, v[130:131]
	s_mov_b32 m0, s29
	s_nop 0
	global_load_lds_dwordx4 v130, s[22:23]
	s_mov_b32 m0, s30
	s_nop 0
	global_load_lds_dwordx4 v132, s[22:23]
	s_waitcnt vmcnt(8)
	s_waitcnt lgkmcnt(0)
	s_barrier
	s_setprio 1
	s_waitcnt lgkmcnt(0)
	v_mfma_f32_16x16x32_bf16 v[62:65], v[158:161], v[198:201], v[62:65]
	v_mfma_f32_16x16x32_bf16 v[58:61], v[166:169], v[198:201], v[58:61]
	v_mfma_f32_16x16x32_bf16 v[46:49], v[158:161], v[206:209], v[46:49]
	v_mfma_f32_16x16x32_bf16 v[42:45], v[166:169], v[206:209], v[42:45]
	v_mfma_f32_16x16x32_bf16 v[34:37], v[158:161], v[214:217], v[34:37]
	v_mfma_f32_16x16x32_bf16 v[26:29], v[166:169], v[214:217], v[26:29]
	v_mfma_f32_16x16x32_bf16 v[18:21], v[158:161], v[222:225], v[18:21]
	v_mfma_f32_16x16x32_bf16 v[10:13], v[166:169], v[222:225], v[10:13]
	v_mfma_f32_16x16x32_bf16 v[62:65], v[162:165], v[202:205], v[62:65]
	v_mfma_f32_16x16x32_bf16 v[58:61], v[170:173], v[202:205], v[58:61]
	v_mfma_f32_16x16x32_bf16 v[46:49], v[162:165], v[210:213], v[46:49]
	v_mfma_f32_16x16x32_bf16 v[42:45], v[170:173], v[210:213], v[42:45]
	v_mfma_f32_16x16x32_bf16 v[34:37], v[162:165], v[218:221], v[34:37]
	v_mfma_f32_16x16x32_bf16 v[26:29], v[170:173], v[218:221], v[26:29]
	v_mfma_f32_16x16x32_bf16 v[18:21], v[162:165], v[226:229], v[18:21]
	v_mfma_f32_16x16x32_bf16 v[10:13], v[170:173], v[226:229], v[10:13]
	s_setprio 0
	s_setprio 1
	v_mfma_f32_16x16x32_bf16 v[54:57], v[182:185], v[198:201], v[54:57]
	v_mfma_f32_16x16x32_bf16 v[50:53], v[190:193], v[198:201], v[50:53]
	v_mfma_f32_16x16x32_bf16 v[38:41], v[182:185], v[206:209], v[38:41]
	v_mfma_f32_16x16x32_bf16 v[30:33], v[190:193], v[206:209], v[30:33]
	v_mfma_f32_16x16x32_bf16 v[22:25], v[182:185], v[214:217], v[22:25]
	v_mfma_f32_16x16x32_bf16 v[14:17], v[190:193], v[214:217], v[14:17]
	v_mfma_f32_16x16x32_bf16 v[6:9], v[182:185], v[222:225], v[6:9]
	v_mfma_f32_16x16x32_bf16 v[2:5], v[190:193], v[222:225], v[2:5]
	v_mfma_f32_16x16x32_bf16 v[54:57], v[186:189], v[202:205], v[54:57]
	v_mfma_f32_16x16x32_bf16 v[50:53], v[194:197], v[202:205], v[50:53]
	v_mfma_f32_16x16x32_bf16 v[38:41], v[186:189], v[210:213], v[38:41]
	v_mfma_f32_16x16x32_bf16 v[30:33], v[194:197], v[210:213], v[30:33]
	v_mfma_f32_16x16x32_bf16 v[22:25], v[186:189], v[218:221], v[22:25]
	v_mfma_f32_16x16x32_bf16 v[14:17], v[194:197], v[218:221], v[14:17]
	v_mfma_f32_16x16x32_bf16 v[6:9], v[186:189], v[226:229], v[6:9]
	v_mfma_f32_16x16x32_bf16 v[2:5], v[194:197], v[226:229], v[2:5]
	s_setprio 0
	s_barrier
	s_add_i32 s52, 0, 0x18000
	s_add_i32 s53, 0, 0x1c000
	v_add_u32_e32 v170, s52, v176
	v_add_u32_e32 v181, s53, v176
	ds_read_b128 v[158:161], v170
	ds_read_b128 v[162:165], v170 offset:1024
	ds_read_b128 v[166:169], v170 offset:2048
	ds_read_b128 v[170:173], v170 offset:3072
	ds_read_b128 v[182:185], v181
	ds_read_b128 v[186:189], v181 offset:1024
	ds_read_b128 v[190:193], v181 offset:2048
	ds_read_b128 v[194:197], v181 offset:3072
	s_add_u32 s16, s22, 0xb0000
	s_addc_u32 s17, s23, 0
	s_mov_b32 m0, s31
	ds_read_b128 v[198:201], v180 offset:32768
	ds_read_b128 v[202:205], v180 offset:33792
	ds_read_b128 v[206:209], v180 offset:34816
	ds_read_b128 v[210:213], v180 offset:35840
	ds_read_b128 v[214:217], v180 offset:36864
	ds_read_b128 v[218:221], v180 offset:37888
	ds_read_b128 v[222:225], v180 offset:38912
	ds_read_b128 v[226:229], v180 offset:39936
	global_load_lds_dwordx4 v130, s[16:17]
	s_mov_b32 m0, s33
	s_nop 0
	global_load_lds_dwordx4 v132, s[16:17]
	s_waitcnt vmcnt(8)
	s_waitcnt lgkmcnt(0)
	s_barrier
	s_setprio 1
	s_waitcnt lgkmcnt(0)
	v_mfma_f32_16x16x32_bf16 v[126:129], v[158:161], v[198:201], v[126:129]
	v_mfma_f32_16x16x32_bf16 v[122:125], v[166:169], v[198:201], v[122:125]
	v_mfma_f32_16x16x32_bf16 v[114:117], v[158:161], v[206:209], v[114:117]
	v_mfma_f32_16x16x32_bf16 v[106:109], v[166:169], v[206:209], v[106:109]
	v_mfma_f32_16x16x32_bf16 v[98:101], v[158:161], v[214:217], v[98:101]
	v_mfma_f32_16x16x32_bf16 v[90:93], v[166:169], v[214:217], v[90:93]
	v_mfma_f32_16x16x32_bf16 v[78:81], v[158:161], v[222:225], v[78:81]
	v_mfma_f32_16x16x32_bf16 v[74:77], v[166:169], v[222:225], v[74:77]
	v_mfma_f32_16x16x32_bf16 v[126:129], v[162:165], v[202:205], v[126:129]
	v_mfma_f32_16x16x32_bf16 v[122:125], v[170:173], v[202:205], v[122:125]
	v_mfma_f32_16x16x32_bf16 v[114:117], v[162:165], v[210:213], v[114:117]
	v_mfma_f32_16x16x32_bf16 v[106:109], v[170:173], v[210:213], v[106:109]
	v_mfma_f32_16x16x32_bf16 v[98:101], v[162:165], v[218:221], v[98:101]
	v_mfma_f32_16x16x32_bf16 v[90:93], v[170:173], v[218:221], v[90:93]
	v_mfma_f32_16x16x32_bf16 v[78:81], v[162:165], v[226:229], v[78:81]
	v_mfma_f32_16x16x32_bf16 v[74:77], v[170:173], v[226:229], v[74:77]
	s_setprio 0
	s_setprio 1
	v_mfma_f32_16x16x32_bf16 v[118:121], v[182:185], v[198:201], v[118:121]
	v_mfma_f32_16x16x32_bf16 v[110:113], v[190:193], v[198:201], v[110:113]
	v_mfma_f32_16x16x32_bf16 v[102:105], v[182:185], v[206:209], v[102:105]
	v_mfma_f32_16x16x32_bf16 v[94:97], v[190:193], v[206:209], v[94:97]
	v_mfma_f32_16x16x32_bf16 v[86:89], v[182:185], v[214:217], v[86:89]
	v_mfma_f32_16x16x32_bf16 v[82:85], v[190:193], v[214:217], v[82:85]
	v_mfma_f32_16x16x32_bf16 v[70:73], v[182:185], v[222:225], v[70:73]
	v_mfma_f32_16x16x32_bf16 v[66:69], v[190:193], v[222:225], v[66:69]
	v_mfma_f32_16x16x32_bf16 v[118:121], v[186:189], v[202:205], v[118:121]
	v_mfma_f32_16x16x32_bf16 v[110:113], v[194:197], v[202:205], v[110:113]
	v_mfma_f32_16x16x32_bf16 v[102:105], v[186:189], v[210:213], v[102:105]
	v_mfma_f32_16x16x32_bf16 v[94:97], v[194:197], v[210:213], v[94:97]
	v_mfma_f32_16x16x32_bf16 v[86:89], v[186:189], v[218:221], v[86:89]
	v_mfma_f32_16x16x32_bf16 v[82:85], v[194:197], v[218:221], v[82:85]
	v_mfma_f32_16x16x32_bf16 v[70:73], v[186:189], v[226:229], v[70:73]
	v_mfma_f32_16x16x32_bf16 v[66:69], v[194:197], v[226:229], v[66:69]
	s_setprio 0
	s_barrier
	s_add_i32 s16, s52, s28
	v_lshl_add_u64 v[174:175], v[174:175], 0, s[10:11]
	s_mov_b32 m0, s16
	ds_read_b128 v[198:201], v180 offset:49152
	ds_read_b128 v[202:205], v180 offset:50176
	ds_read_b128 v[206:209], v180 offset:51200
	ds_read_b128 v[210:213], v180 offset:52224
	ds_read_b128 v[214:217], v180 offset:53248
	ds_read_b128 v[218:221], v180 offset:54272
	ds_read_b128 v[222:225], v180 offset:55296
	ds_read_b128 v[226:229], v180 offset:56320
	global_load_lds_dwordx4 v[174:175], off
	s_add_i32 m0, s16, 0x2000
	s_add_u32 s16, s20, 0xb0080
	v_lshl_add_u64 v[174:175], v[230:231], 0, s[10:11]
	s_addc_u32 s17, s21, 0
	s_add_i32 s20, s53, s28
	global_load_lds_dwordx4 v[174:175], off
	s_mov_b32 m0, s20
	s_nop 0
	global_load_lds_dwordx4 v130, s[16:17]
	s_add_i32 m0, s20, 0x2000
	s_nop 0
	global_load_lds_dwordx4 v132, s[16:17]
	v_lshl_add_u64 v[174:175], v[232:233], 0, s[10:11]
	s_mov_b32 m0, s39
	s_nop 0
	global_load_lds_dwordx4 v[174:175], off
	v_lshl_add_u64 v[174:175], v[234:235], 0, s[10:11]
	s_mov_b32 m0, s40
	s_nop 0
	global_load_lds_dwordx4 v[174:175], off
	s_waitcnt vmcnt(8)
	s_waitcnt lgkmcnt(0)
	s_barrier
	s_setprio 1
	s_waitcnt lgkmcnt(0)
	v_mfma_f32_16x16x32_bf16 v[62:65], v[158:161], v[198:201], v[62:65]
	v_mfma_f32_16x16x32_bf16 v[58:61], v[166:169], v[198:201], v[58:61]
	v_mfma_f32_16x16x32_bf16 v[46:49], v[158:161], v[206:209], v[46:49]
	v_mfma_f32_16x16x32_bf16 v[42:45], v[166:169], v[206:209], v[42:45]
	v_mfma_f32_16x16x32_bf16 v[34:37], v[158:161], v[214:217], v[34:37]
	v_mfma_f32_16x16x32_bf16 v[26:29], v[166:169], v[214:217], v[26:29]
	v_mfma_f32_16x16x32_bf16 v[18:21], v[158:161], v[222:225], v[18:21]
	v_mfma_f32_16x16x32_bf16 v[10:13], v[166:169], v[222:225], v[10:13]
	v_mfma_f32_16x16x32_bf16 v[62:65], v[162:165], v[202:205], v[62:65]
	v_mfma_f32_16x16x32_bf16 v[58:61], v[170:173], v[202:205], v[58:61]
	v_mfma_f32_16x16x32_bf16 v[46:49], v[162:165], v[210:213], v[46:49]
	v_mfma_f32_16x16x32_bf16 v[42:45], v[170:173], v[210:213], v[42:45]
	v_mfma_f32_16x16x32_bf16 v[34:37], v[162:165], v[218:221], v[34:37]
	v_mfma_f32_16x16x32_bf16 v[26:29], v[170:173], v[218:221], v[26:29]
	v_mfma_f32_16x16x32_bf16 v[18:21], v[162:165], v[226:229], v[18:21]
	v_mfma_f32_16x16x32_bf16 v[10:13], v[170:173], v[226:229], v[10:13]
	s_setprio 0
	s_setprio 1
	v_mfma_f32_16x16x32_bf16 v[54:57], v[182:185], v[198:201], v[54:57]
	v_mfma_f32_16x16x32_bf16 v[50:53], v[190:193], v[198:201], v[50:53]
	v_mfma_f32_16x16x32_bf16 v[38:41], v[182:185], v[206:209], v[38:41]
	v_mfma_f32_16x16x32_bf16 v[30:33], v[190:193], v[206:209], v[30:33]
	v_mfma_f32_16x16x32_bf16 v[22:25], v[182:185], v[214:217], v[22:25]
	v_mfma_f32_16x16x32_bf16 v[14:17], v[190:193], v[214:217], v[14:17]
	v_mfma_f32_16x16x32_bf16 v[6:9], v[182:185], v[222:225], v[6:9]
	v_mfma_f32_16x16x32_bf16 v[2:5], v[190:193], v[222:225], v[2:5]
	v_mfma_f32_16x16x32_bf16 v[54:57], v[186:189], v[202:205], v[54:57]
	v_mfma_f32_16x16x32_bf16 v[50:53], v[194:197], v[202:205], v[50:53]
	v_mfma_f32_16x16x32_bf16 v[38:41], v[186:189], v[210:213], v[38:41]
	v_mfma_f32_16x16x32_bf16 v[30:33], v[194:197], v[210:213], v[30:33]
	v_mfma_f32_16x16x32_bf16 v[22:25], v[186:189], v[218:221], v[22:25]
	v_mfma_f32_16x16x32_bf16 v[14:17], v[194:197], v[218:221], v[14:17]
	v_mfma_f32_16x16x32_bf16 v[6:9], v[186:189], v[226:229], v[6:9]
	v_mfma_f32_16x16x32_bf16 v[2:5], v[194:197], v[226:229], v[2:5]
	s_setprio 0
	s_barrier
	s_add_i32 s51, s51, 2
	s_add_u32 s2, s2, 0x100
	s_addc_u32 s50, s50, 0
	s_cmp_gt_u32 s51, 41
	s_mov_b64 s[16:17], s[18:19]
	s_cbranch_scc0 .LBB0_2583
	s_and_b64 vcc, exec, s[12:13]
	s_cbranch_vccz .LBB0_2586
	s_barrier
